# attention unrolled loop 12 steps per back-edge; GEMM K-loop 4 K-tiles per back-edge (fewer taken branches)
# baseline (speedup 1.0000x reference)
; #define WAIT_BAR(N) asm volatile("s_waitcnt vmcnt(" #N ") lgkmcnt(0)\n\ts_barrier":::"memory")
;   #define DMA_K(t,slot) glds16(ksrc+(long)(t)*4096,(unsigned)__builtin_amdgcn_readfirstlane(kdst+(slot)))
;   #define DMA_V(t,slot) glds16(vsrc+(long)(t)*4096,(unsigned)__builtin_amdgcn_readfirstlane(vdst+(slot)))
;   #define CMASK(P0,P1,t) do{}while(0)
;   #define ROT() do{sl_prev=sl_cur;sl_cur=sl_next;sl_next=(sl_next==(NSLOT-1)*SLOTB)?0:sl_next+SLOTB;}while(0)
;   #define CMASK(P0,P1,t) do{}while(0)
;   #define CMASK(P0,P1,t) do{}while(0)
; template<int THRL,bool FIXREF> __device__ __forceinline__ void attn_unit(const float*gq,const float*tab,const int tq0,const bf16*Qw0,const bf16*__restrict__ Kl,const bf16*__restrict__ Vl,const int NT,bf16*Ow0,char*shm){
;     ...
;   float mhat=0.f,l_reg=0.f;f32x16 o[2];o[0]=f32x16{};o[1]=f32x16{};f32x16 negm=f32x16{};asm volatile("":"+v"(negm));
;     ...
;   bool resc=false;
;     ...
;   f32x16 pA0,pA1,pB0,pB1;
;   int sl_prev=0,sl_cur=0,sl_next=SLOTB;
;     ...
;   DMA_K(2,2*SLOTB);
;   WAIT_BAR(3);
;   qkt(pA0,pA1,Kbase,qr,negm,r32,hi);asm volatile("s_nop 15\n\ts_nop 7":"+v"(pA0),"+v"(pA1));CMASK(pA0,pA1,0);
;   START(pA0,pA1);
;   _Pragma("unroll") for(int r=0;r<16;++r)pA1[r]=__builtin_amdgcn_exp2f(pA1[r]);
;   WAIT_BAR(0);
;   DMA_K(3,0);DMA_V(1,SLOTB);
;   ROT();
;   kload8(kf,kp0+sl_cur);
;   WAIT_BAR(2);
.LBB0_276:
	v_lshlrev_b32_e32 v0, 10, v228
	v_lshlrev_b32_e32 v2, 4, v227
	v_add3_u32 v230, 0, v0, v2
	v_mov_b32_e32 v2, v1
	v_mov_b32_e32 v3, v1
	v_mov_b32_e32 v4, v1
	v_mov_b32_e32 v5, v1
	v_mov_b32_e32 v6, v1
	v_mov_b32_e32 v7, v1
	v_mov_b32_e32 v8, v1
	v_mov_b32_e32 v9, v1
	v_mov_b32_e32 v10, v1
	v_mov_b32_e32 v11, v1
	v_mov_b32_e32 v12, v1
	v_mov_b32_e32 v13, v1
	v_mov_b32_e32 v14, v1
	v_mov_b32_e32 v15, v1
	s_cmp_lg_u32 0, -1
	v_mov_b32_e32 v0, v1
	v_mov_b64_e32 v[16:17], v[14:15]
	s_cselect_b32 s4, 0, 0
	v_mov_b64_e32 v[14:15], v[12:13]
	v_mov_b64_e32 v[12:13], v[10:11]
	v_mov_b64_e32 v[10:11], v[8:9]
	v_mov_b64_e32 v[8:9], v[6:7]
	v_mov_b64_e32 v[6:7], v[4:5]
	v_mov_b64_e32 v[4:5], v[2:3]
	v_mov_b64_e32 v[2:3], v[0:1]
	s_add_i32 s5, s4, s7
	v_lshl_add_u64 v[18:19], v[194:195], 0, s[16:17]
	s_add_i32 s4, s5, 0x4000
	s_mov_b32 s6, m0
	s_mov_b32 m0, s4
	s_nop 0
	global_load_lds_dwordx4 v[18:19], off
	s_mov_b32 m0, s6
	s_waitcnt vmcnt(3) lgkmcnt(0)
	s_barrier
	ds_read_b128 v[18:21], v230
	ds_read_b128 v[86:89], v230 offset:512
	v_cvt_pk_bf16_f32 v158, v22, v23
	v_cvt_pk_bf16_f32 v159, v24, v25
	v_cvt_pk_bf16_f32 v160, v38, v39
	v_cvt_pk_bf16_f32 v161, v40, v41
	v_cvt_pk_bf16_f32 v150, v54, v55
	v_cvt_pk_bf16_f32 v151, v56, v57
	s_waitcnt lgkmcnt(1)
	v_mfma_f32_32x32x16_bf16 v[34:49], v[18:21], v[158:161], v[2:17]
	ds_read_b128 v[54:57], v230 offset:2560
	v_cvt_pk_bf16_f32 v152, v58, v59
	v_cvt_pk_bf16_f32 v153, v62, v63
	v_cvt_pk_bf16_f32 v142, v82, v69
	v_cvt_pk_bf16_f32 v145, v76, v71
	ds_read_b128 v[68:71], v230 offset:4608
	v_cvt_pk_bf16_f32 v143, v80, v73
	s_waitcnt lgkmcnt(2)
	v_mfma_f32_32x32x16_bf16 v[18:33], v[86:89], v[158:161], v[2:17]
	ds_read_b128 v[86:89], v230 offset:2048
	v_cvt_pk_bf16_f32 v144, v78, v75
	v_cvt_pk_bf16_f32 v134, v52, v53
	v_cvt_pk_bf16_f32 v135, v60, v61
	v_cvt_pk_bf16_f32 v136, v66, v67
	v_cvt_pk_bf16_f32 v137, v64, v65
	s_mov_b64 s[14:15], 0x6000
	s_waitcnt lgkmcnt(2)
	v_mfma_f32_32x32x16_bf16 v[18:33], v[54:57], v[150:153], v[18:33]
	ds_read_b128 v[54:57], v230 offset:4096
	s_add_i32 s5, s5, 0x8000
	v_lshlrev_b32_e32 v0, 1, v84
	v_and_b32_e32 v231, 32, v0
	v_lshlrev_b32_e32 v0, 3, v84
	v_lshlrev_b32_e32 v52, 4, v84
	v_and_b32_e32 v52, 0xc0, v52
	s_waitcnt lgkmcnt(1)
	v_mfma_f32_32x32x16_bf16 v[34:49], v[86:89], v[150:153], v[34:49]
	v_and_b32_e32 v232, 24, v0
	v_lshl_or_b32 v229, v228, 8, v52
	v_add_u32_e32 v52, 0, v231
	s_mov_b32 s10, 1
	v_add3_u32 v233, v52, v232, v229
	s_mov_b32 s4, 0
	s_movk_i32 s31, 0x4000
	s_waitcnt lgkmcnt(0)
	v_mfma_f32_32x32x16_bf16 v[34:49], v[54:57], v[142:145], v[34:49]
	ds_read_b128 v[54:57], v230 offset:6656
	ds_read_b128 v[72:75], v230 offset:6144
	s_cmp_lt_u32 s55, 7
	v_mfma_f32_32x32x16_bf16 v[18:33], v[68:71], v[142:145], v[18:33]
	s_waitcnt lgkmcnt(0)
	v_mfma_f32_32x32x16_bf16 v[34:49], v[72:75], v[134:137], v[34:49]
	v_mfma_f32_32x32x16_bf16 v[18:33], v[54:57], v[134:137], v[18:33]
	s_nop 15
	s_nop 7
	s_waitcnt vmcnt(0) lgkmcnt(0)
	s_barrier
	s_nop 10
	v_exp_f32_e32 v82, v34
	v_exp_f32_e32 v83, v35
	v_exp_f32_e32 v66, v18
	v_exp_f32_e32 v67, v19
	v_lshl_add_u64 v[18:19], v[194:195], 0, s[14:15]
	s_mov_b32 s6, m0
	s_mov_b32 m0, s18
	s_nop 0
	global_load_lds_dwordx4 v[18:19], off
	s_mov_b32 m0, s6
	s_mov_b64 s[6:7], 0x2000
	v_lshl_add_u64 v[196:197], v[50:51], 0, s[6:7]
	s_mov_b32 s6, m0
	s_mov_b32 m0, s5
	s_nop 0
	global_load_lds_dwordx4 v[196:197], off
	s_mov_b32 m0, s6
	ds_read_b128 v[190:193], v230 offset:8192
	ds_read_b128 v[186:189], v230 offset:8704
	ds_read_b128 v[182:185], v230 offset:10240
	ds_read_b128 v[178:181], v230 offset:10752
	ds_read_b128 v[174:177], v230 offset:12288
	ds_read_b128 v[170:173], v230 offset:12800
	ds_read_b128 v[166:169], v230 offset:14336
	ds_read_b128 v[162:165], v230 offset:14848
	v_exp_f32_e32 v84, v36
	v_exp_f32_e32 v85, v37
	v_exp_f32_e32 v86, v38
	v_exp_f32_e32 v87, v39
	v_exp_f32_e32 v88, v40
	v_exp_f32_e32 v89, v41
	v_exp_f32_e32 v90, v42
	v_exp_f32_e32 v91, v43
	v_exp_f32_e32 v92, v44
	v_exp_f32_e32 v93, v45
	v_exp_f32_e32 v94, v46
	v_exp_f32_e32 v95, v47
	v_exp_f32_e32 v96, v48
	v_exp_f32_e32 v97, v49
	v_exp_f32_e32 v68, v20
	v_exp_f32_e32 v69, v21
	v_exp_f32_e32 v70, v22
	v_exp_f32_e32 v71, v23
	v_exp_f32_e32 v72, v24
	v_exp_f32_e32 v73, v25
	v_exp_f32_e32 v74, v26
	v_exp_f32_e32 v75, v27
	v_exp_f32_e32 v76, v28
	v_exp_f32_e32 v77, v29
	v_exp_f32_e32 v78, v30
	v_exp_f32_e32 v79, v31
	v_exp_f32_e32 v80, v32
	v_exp_f32_e32 v81, v33
	s_waitcnt vmcnt(2) lgkmcnt(0)
	s_barrier
	s_cbranch_scc1 .LBB0_287
	v_lshl_add_u64 v[56:57], v[50:51], 0, s[14:15]
	s_mov_b64 s[4:5], 0xa000
	v_mov_b32_e32 v50, 0
	v_lshl_add_u64 v[58:59], v[194:195], 0, s[4:5]
	s_movk_i32 s30, 0x2000
	s_mov_b32 s7, 0
	s_mov_b32 s10, 6
	v_lshlrev_b32_e32 v240, 4, v224
	v_sub_u32_e32 v241, v56, v58
	v_readfirstlane_b32 s100, v58
	v_readfirstlane_b32 s101, v59
	v_add_u32_e32 v241, v241, v240
	s_nop 3
	s_sub_u32 s100, s100, 0x2000
	s_subb_u32 s101, s101, 0
	v_mov_b32_e32 v18, 0
	v_mov_b32_e32 v19, v50
	v_mov_b32_e32 v20, v50
	v_mov_b32_e32 v21, v50
	v_mov_b32_e32 v22, v50
	v_mov_b32_e32 v23, v50
	v_mov_b32_e32 v24, v50
	v_mov_b32_e32 v25, v50
	v_mov_b32_e32 v26, v50
	v_mov_b32_e32 v27, v50
	v_mov_b32_e32 v28, v50
	v_mov_b32_e32 v29, v50
	v_mov_b32_e32 v30, v50
	v_mov_b32_e32 v31, v50
	v_mov_b32_e32 v32, v50
	v_mov_b32_e32 v33, v50
	v_mov_b32_e32 v34, 0
	v_mov_b32_e32 v35, v50
	v_mov_b32_e32 v36, v50
	v_mov_b32_e32 v37, v50
	v_mov_b32_e32 v38, v50
	v_mov_b32_e32 v39, v50
	v_mov_b32_e32 v40, v50
	v_mov_b32_e32 v41, v50
	v_mov_b32_e32 v42, v50
	v_mov_b32_e32 v43, v50
	v_mov_b32_e32 v44, v50
	v_mov_b32_e32 v45, v50
	v_mov_b32_e32 v46, v50
	v_mov_b32_e32 v47, v50
	v_mov_b32_e32 v48, v50
	v_mov_b32_e32 v49, v50
	s_add_i32 s5, s10, 10
	s_cmp_lt_u32 s5, s55
	s_cbranch_scc0 .LBB0_278
; #define WAIT_BAR(N) asm volatile("s_waitcnt vmcnt(" #N ") lgkmcnt(0)\n\ts_barrier":::"memory")
;   #define RESC() do{ if(resc){ asm volatile("s_waitcnt lgkmcnt(0)":::"memory"); \
;       _Pragma("unroll") for(int d_=0;d_<2;++d_) _Pragma("unroll") for(int r=0;r<16;++r)o[d_][r]*=wsf[crow(r,hi)]; } }while(0)
;   #define ROT() do{sl_prev=sl_cur;sl_cur=sl_next;sl_next=(sl_next==(NSLOT-1)*SLOTB)?0:sl_next+SLOTB;}while(0)
; template<int THRL,bool FIXREF> __device__ __forceinline__ void attn_unit(const float*gq,const float*tab,const int tq0,const bf16*Qw0,const bf16*__restrict__ Kl,const bf16*__restrict__ Vl,const int NT,bf16*Ow0,char*shm){
;     ...
;   int t=1;
;     ...
;   for(;t+5<NT;t+=2){
;     STEP(pB0,pB1,pA0,pA1,t,true,true,true);     WAIT_BAR(2); RESC(); ROT();
;     STEP(pA0,pA1,pB0,pB1,t+1,true,true,true);   WAIT_BAR(2); RESC(); ROT();
.Lattn6:
	ds_read_b64_tr_b16 v[52:53], v233 offset:24576
	ds_read_b64_tr_b16 v[54:55], v233 offset:25088
	v_add_f32_e32 v60, v82, v83
	v_add_f32_e32 v60, v84, v60
	v_add_f32_e32 v60, v85, v60
	v_add_f32_e32 v60, v86, v60
	v_add_f32_e32 v64, v87, v60
	v_cvt_pk_bf16_f32 v154, v82, v83
	v_cvt_pk_bf16_f32 v155, v84, v85
	s_waitcnt lgkmcnt(9)
	v_mfma_f32_32x32x16_bf16 v[114:129], v[190:193], v[158:161], v[2:17]
	ds_read_b64_tr_b16 v[60:61], v233 offset:28672
	ds_read_b64_tr_b16 v[62:63], v233 offset:29184
	v_add_f32_e32 v64, v88, v64
	v_add_f32_e32 v64, v89, v64
	v_add_f32_e32 v64, v90, v64
	v_add_f32_e32 v64, v91, v64
	v_cvt_pk_bf16_f32 v156, v86, v87
	v_cvt_pk_bf16_f32 v157, v88, v89
	s_waitcnt lgkmcnt(10)
	v_mfma_f32_32x32x16_bf16 v[98:113], v[186:189], v[158:161], v[2:17]
	ds_read_b64_tr_b16 v[82:83], v233 offset:25600
	ds_read_b64_tr_b16 v[84:85], v233 offset:26112
	v_add_f32_e32 v64, v92, v64
	v_add_f32_e32 v64, v93, v64
	v_add_f32_e32 v64, v94, v64
	v_add_f32_e32 v64, v95, v64
	v_cvt_pk_bf16_f32 v146, v90, v91
	v_cvt_pk_bf16_f32 v147, v92, v93
	s_waitcnt lgkmcnt(11)
	v_mfma_f32_32x32x16_bf16 v[114:129], v[182:185], v[150:153], v[114:129]
	ds_read_b64_tr_b16 v[86:87], v233 offset:29696
	ds_read_b64_tr_b16 v[88:89], v233 offset:30208
	v_add_f32_e32 v64, v96, v64
	v_add_f32_e32 v64, v97, v64
	v_add_f32_e32 v64, v66, v64
	v_add_f32_e32 v64, v67, v64
	v_cvt_pk_bf16_f32 v148, v94, v95
	v_cvt_pk_bf16_f32 v149, v96, v97
	s_waitcnt lgkmcnt(12)
	v_mfma_f32_32x32x16_bf16 v[98:113], v[178:181], v[150:153], v[98:113]
	ds_read_b64_tr_b16 v[90:91], v233 offset:26624
	ds_read_b64_tr_b16 v[92:93], v233 offset:27136
	v_add_f32_e32 v64, v68, v64
	v_add_f32_e32 v64, v69, v64
	v_add_f32_e32 v64, v70, v64
	v_add_f32_e32 v94, v71, v64
	v_cvt_pk_bf16_f32 v138, v66, v67
	v_cvt_pk_bf16_f32 v139, v68, v69
	s_waitcnt lgkmcnt(13)
	v_mfma_f32_32x32x16_bf16 v[114:129], v[174:177], v[142:145], v[114:129]
	ds_read_b64_tr_b16 v[64:65], v233 offset:30720
	ds_read_b64_tr_b16 v[66:67], v233 offset:31232
	v_add_f32_e32 v68, v72, v94
	v_add_f32_e32 v68, v73, v68
	v_add_f32_e32 v68, v74, v68
	v_add_f32_e32 v94, v75, v68
	v_cvt_pk_bf16_f32 v140, v70, v71
	v_cvt_pk_bf16_f32 v141, v72, v73
	s_waitcnt lgkmcnt(14)
	v_mfma_f32_32x32x16_bf16 v[98:113], v[170:173], v[142:145], v[98:113]
	ds_read_b64_tr_b16 v[68:69], v233 offset:27648
	ds_read_b64_tr_b16 v[70:71], v233 offset:28160
	v_add_f32_e32 v72, v76, v94
	v_add_f32_e32 v72, v77, v72
	v_add_f32_e32 v72, v78, v72
	v_add_f32_e32 v94, v79, v72
	v_cvt_pk_bf16_f32 v130, v74, v75
	v_cvt_pk_bf16_f32 v131, v76, v77
	s_waitcnt lgkmcnt(14)
	v_mfma_f32_32x32x16_bf16 v[114:129], v[166:169], v[134:137], v[114:129]
	ds_read_b64_tr_b16 v[72:73], v233 offset:31744
	ds_read_b64_tr_b16 v[74:75], v233 offset:32256
	v_add_f32_e32 v51, v80, v94
	v_add_f32_e32 v51, v81, v51
	v_cvt_pk_bf16_f32 v132, v78, v79
	v_cvt_pk_bf16_f32 v133, v80, v81
	v_mfma_f32_32x32x16_bf16 v[98:113], v[162:165], v[134:137], v[98:113]
	s_add_i32 m0, s18, 0x2000
	s_nop 0
	global_load_lds_dwordx4 v240, s[100:101]
	s_add_i32 m0, s19, 0x4000
	s_nop 0
	global_load_lds_dwordx4 v241, s[100:101]
	s_waitcnt lgkmcnt(14)
	v_mfma_f32_32x32x16_bf16 v[18:33], v[154:157], v[52:55], v[18:33]
	s_add_u32 s100, s100, 0x2000
	s_addc_u32 s101, s101, 0
	v_exp_f32_e32 v114, v114
	v_exp_f32_e32 v115, v115
	v_exp_f32_e32 v116, v116
	v_exp_f32_e32 v117, v117
	s_waitcnt lgkmcnt(12)
	v_mfma_f32_32x32x16_bf16 v[34:49], v[154:157], v[60:63], v[34:49]
	v_exp_f32_e32 v118, v118
	v_exp_f32_e32 v119, v119
	v_exp_f32_e32 v120, v120
	v_exp_f32_e32 v121, v121
	ds_read_b128 v[60:63], v230 offset:16384
	ds_read_b128 v[162:165], v230 offset:16896
	s_waitcnt lgkmcnt(12)
	v_mfma_f32_32x32x16_bf16 v[18:33], v[146:149], v[82:85], v[18:33]
	v_exp_f32_e32 v122, v122
	v_exp_f32_e32 v123, v123
	v_exp_f32_e32 v124, v124
	v_exp_f32_e32 v125, v125
	ds_read_b128 v[166:169], v230 offset:18432
	ds_read_b128 v[170:173], v230 offset:18944
	s_waitcnt lgkmcnt(12)
	v_mfma_f32_32x32x16_bf16 v[34:49], v[146:149], v[86:89], v[34:49]
	v_exp_f32_e32 v126, v126
	v_exp_f32_e32 v127, v127
	v_exp_f32_e32 v128, v128
	v_exp_f32_e32 v129, v129
	ds_read_b128 v[174:177], v230 offset:20480
	ds_read_b128 v[178:181], v230 offset:20992
	s_waitcnt lgkmcnt(12)
	v_mfma_f32_32x32x16_bf16 v[18:33], v[138:141], v[90:93], v[18:33]
	v_exp_f32_e32 v98, v98
	v_exp_f32_e32 v99, v99
	v_exp_f32_e32 v100, v100
	v_exp_f32_e32 v101, v101
	ds_read_b128 v[182:185], v230 offset:22528
	ds_read_b128 v[52:55], v230 offset:23040
	s_waitcnt lgkmcnt(12)
	v_mfma_f32_32x32x16_bf16 v[34:49], v[138:141], v[64:67], v[34:49]
	v_exp_f32_e32 v102, v102
	v_exp_f32_e32 v103, v103
	v_exp_f32_e32 v104, v104
	v_exp_f32_e32 v105, v105
	s_waitcnt lgkmcnt(10)
	v_mfma_f32_32x32x16_bf16 v[18:33], v[130:133], v[68:71], v[18:33]
	v_exp_f32_e32 v106, v106
	v_exp_f32_e32 v107, v107
	v_exp_f32_e32 v108, v108
	v_exp_f32_e32 v109, v109
	s_waitcnt lgkmcnt(8)
	v_mfma_f32_32x32x16_bf16 v[34:49], v[130:133], v[72:75], v[34:49]
	v_exp_f32_e32 v110, v110
	v_exp_f32_e32 v111, v111
	v_exp_f32_e32 v112, v112
	v_exp_f32_e32 v113, v113
	s_waitcnt vmcnt(2) lgkmcnt(0)
	s_barrier
; #define WAIT_BAR(N) asm volatile("s_waitcnt vmcnt(" #N ") lgkmcnt(0)\n\ts_barrier":::"memory")
;   #define RESC() do{ if(resc){ asm volatile("s_waitcnt lgkmcnt(0)":::"memory"); \
;       _Pragma("unroll") for(int d_=0;d_<2;++d_) _Pragma("unroll") for(int r=0;r<16;++r)o[d_][r]*=wsf[crow(r,hi)]; } }while(0)
;   #define ROT() do{sl_prev=sl_cur;sl_cur=sl_next;sl_next=(sl_next==(NSLOT-1)*SLOTB)?0:sl_next+SLOTB;}while(0)
; template<int THRL,bool FIXREF> __device__ __forceinline__ void attn_unit(const float*gq,const float*tab,const int tq0,const bf16*Qw0,const bf16*__restrict__ Kl,const bf16*__restrict__ Vl,const int NT,bf16*Ow0,char*shm){
;     ...
;   int t=1;
;     ...
;   for(;t+5<NT;t+=2){
;     STEP(pB0,pB1,pA0,pA1,t,true,true,true);     WAIT_BAR(2); RESC(); ROT();
;     STEP(pA0,pA1,pB0,pB1,t+1,true,true,true);   WAIT_BAR(2); RESC(); ROT();
	ds_read_b64_tr_b16 v[186:187], v233 offset:32768
	ds_read_b64_tr_b16 v[188:189], v233 offset:33280
	s_waitcnt lgkmcnt(9)
	v_mfma_f32_32x32x16_bf16 v[82:97], v[60:63], v[158:161], v[2:17]
	v_add_f32_e32 v65, v114, v115
	v_add_f32_e32 v65, v116, v65
	v_add_f32_e32 v65, v117, v65
	v_add_f32_e32 v65, v118, v65
	v_add_f32_e32 v65, v119, v65
	v_cvt_pk_bf16_f32 v154, v114, v115
	v_cvt_pk_bf16_f32 v155, v116, v117
	ds_read_b64_tr_b16 v[60:61], v233 offset:36864
	ds_read_b64_tr_b16 v[62:63], v233 offset:37376
	s_waitcnt lgkmcnt(10)
	v_mfma_f32_32x32x16_bf16 v[66:81], v[162:165], v[158:161], v[2:17]
	v_add_f32_e32 v65, v120, v65
	v_add_f32_e32 v65, v121, v65
	v_add_f32_e32 v65, v122, v65
	v_add_f32_e32 v65, v123, v65
	v_cvt_pk_bf16_f32 v156, v118, v119
	v_cvt_pk_bf16_f32 v157, v120, v121
	ds_read_b64_tr_b16 v[114:115], v233 offset:33792
	ds_read_b64_tr_b16 v[116:117], v233 offset:34304
	s_waitcnt lgkmcnt(11)
	v_mfma_f32_32x32x16_bf16 v[82:97], v[166:169], v[150:153], v[82:97]
	v_add_f32_e32 v65, v124, v65
	v_add_f32_e32 v65, v125, v65
	v_add_f32_e32 v65, v126, v65
	v_add_f32_e32 v65, v127, v65
	v_cvt_pk_bf16_f32 v146, v122, v123
	v_cvt_pk_bf16_f32 v147, v124, v125
	ds_read_b64_tr_b16 v[118:119], v233 offset:37888
	ds_read_b64_tr_b16 v[120:121], v233 offset:38400
	s_waitcnt lgkmcnt(12)
	v_mfma_f32_32x32x16_bf16 v[66:81], v[170:173], v[150:153], v[66:81]
	v_add_f32_e32 v65, v128, v65
	v_add_f32_e32 v65, v129, v65
	v_add_f32_e32 v65, v98, v65
	v_add_f32_e32 v65, v99, v65
	v_cvt_pk_bf16_f32 v148, v126, v127
	v_cvt_pk_bf16_f32 v149, v128, v129
	ds_read_b64_tr_b16 v[122:123], v233 offset:34816
	ds_read_b64_tr_b16 v[124:125], v233 offset:35328
	s_waitcnt lgkmcnt(13)
	v_mfma_f32_32x32x16_bf16 v[82:97], v[174:177], v[142:145], v[82:97]
	v_add_f32_e32 v65, v100, v65
	v_add_f32_e32 v65, v101, v65
	v_add_f32_e32 v65, v102, v65
	v_add_f32_e32 v65, v103, v65
	v_cvt_pk_bf16_f32 v138, v98, v99
	v_cvt_pk_bf16_f32 v139, v100, v101
	ds_read_b64_tr_b16 v[98:99], v233 offset:38912
	ds_read_b64_tr_b16 v[100:101], v233 offset:39424
	s_waitcnt lgkmcnt(14)
	v_mfma_f32_32x32x16_bf16 v[66:81], v[178:181], v[142:145], v[66:81]
	v_add_f32_e32 v65, v104, v65
	v_add_f32_e32 v65, v105, v65
	v_add_f32_e32 v65, v106, v65
	v_add_f32_e32 v65, v107, v65
	v_cvt_pk_bf16_f32 v140, v102, v103
	v_cvt_pk_bf16_f32 v141, v104, v105
	ds_read_b64_tr_b16 v[102:103], v233 offset:35840
	ds_read_b64_tr_b16 v[104:105], v233 offset:36352
	s_waitcnt lgkmcnt(14)
	v_mfma_f32_32x32x16_bf16 v[82:97], v[182:185], v[134:137], v[82:97]
	v_add_f32_e32 v65, v108, v65
	v_add_f32_e32 v65, v109, v65
	v_add_f32_e32 v65, v110, v65
	v_add_f32_e32 v65, v111, v65
	v_cvt_pk_bf16_f32 v130, v106, v107
	v_cvt_pk_bf16_f32 v131, v108, v109
	ds_read_b64_tr_b16 v[106:107], v233 offset:39936
	ds_read_b64_tr_b16 v[108:109], v233 offset:40448
	v_mfma_f32_32x32x16_bf16 v[66:81], v[52:55], v[134:137], v[66:81]
	v_add_f32_e32 v52, v112, v65
	v_add_f32_e32 v52, v113, v52
	v_cvt_pk_bf16_f32 v132, v110, v111
	v_cvt_pk_bf16_f32 v133, v112, v113
	s_add_i32 m0, s18, 0x4000
	s_nop 0
	global_load_lds_dwordx4 v240, s[100:101]
	s_mov_b32 m0, s19
	s_nop 0
	global_load_lds_dwordx4 v241, s[100:101]
	s_waitcnt lgkmcnt(14)
	v_mfma_f32_32x32x16_bf16 v[18:33], v[154:157], v[186:189], v[18:33]
	s_add_u32 s100, s100, 0x2000
	s_addc_u32 s101, s101, 0
	v_exp_f32_e32 v82, v82
	v_exp_f32_e32 v83, v83
	v_exp_f32_e32 v84, v84
	v_exp_f32_e32 v85, v85
	s_waitcnt lgkmcnt(12)
	v_mfma_f32_32x32x16_bf16 v[34:49], v[154:157], v[60:63], v[34:49]
	v_exp_f32_e32 v86, v86
	v_exp_f32_e32 v87, v87
	v_exp_f32_e32 v88, v88
	v_exp_f32_e32 v89, v89
	ds_read_b128 v[190:193], v230
	ds_read_b128 v[186:189], v230 offset:512
	s_waitcnt lgkmcnt(12)
	v_mfma_f32_32x32x16_bf16 v[18:33], v[146:149], v[114:117], v[18:33]
	v_exp_f32_e32 v90, v90
	v_exp_f32_e32 v91, v91
	v_exp_f32_e32 v92, v92
	v_exp_f32_e32 v93, v93
	ds_read_b128 v[182:185], v230 offset:2048
	ds_read_b128 v[178:181], v230 offset:2560
	s_waitcnt lgkmcnt(12)
	v_mfma_f32_32x32x16_bf16 v[34:49], v[146:149], v[118:121], v[34:49]
	v_exp_f32_e32 v94, v94
	v_exp_f32_e32 v95, v95
	v_exp_f32_e32 v96, v96
	v_exp_f32_e32 v97, v97
	ds_read_b128 v[174:177], v230 offset:4096
	ds_read_b128 v[170:173], v230 offset:4608
	s_waitcnt lgkmcnt(12)
	v_mfma_f32_32x32x16_bf16 v[18:33], v[138:141], v[122:125], v[18:33]
	v_exp_f32_e32 v66, v66
	v_exp_f32_e32 v67, v67
	v_exp_f32_e32 v68, v68
	v_exp_f32_e32 v69, v69
	ds_read_b128 v[166:169], v230 offset:6144
	ds_read_b128 v[162:165], v230 offset:6656
	s_waitcnt lgkmcnt(12)
	v_mfma_f32_32x32x16_bf16 v[34:49], v[138:141], v[98:101], v[34:49]
	v_exp_f32_e32 v70, v70
	v_exp_f32_e32 v71, v71
	v_exp_f32_e32 v72, v72
	v_exp_f32_e32 v73, v73
	s_waitcnt lgkmcnt(10)
	v_mfma_f32_32x32x16_bf16 v[18:33], v[130:133], v[102:105], v[18:33]
	v_exp_f32_e32 v74, v74
	v_exp_f32_e32 v75, v75
	v_exp_f32_e32 v76, v76
	v_exp_f32_e32 v77, v77
	s_waitcnt lgkmcnt(8)
	v_mfma_f32_32x32x16_bf16 v[34:49], v[130:133], v[106:109], v[34:49]
	v_exp_f32_e32 v78, v78
	v_exp_f32_e32 v79, v79
	v_exp_f32_e32 v80, v80
	v_exp_f32_e32 v81, v81
	s_waitcnt vmcnt(2) lgkmcnt(0)
	s_barrier
; #define WAIT_BAR(N) asm volatile("s_waitcnt vmcnt(" #N ") lgkmcnt(0)\n\ts_barrier":::"memory")
;   #define RESC() do{ if(resc){ asm volatile("s_waitcnt lgkmcnt(0)":::"memory"); \
;       _Pragma("unroll") for(int d_=0;d_<2;++d_) _Pragma("unroll") for(int r=0;r<16;++r)o[d_][r]*=wsf[crow(r,hi)]; } }while(0)
;   #define ROT() do{sl_prev=sl_cur;sl_cur=sl_next;sl_next=(sl_next==(NSLOT-1)*SLOTB)?0:sl_next+SLOTB;}while(0)
; template<int THRL,bool FIXREF> __device__ __forceinline__ void attn_unit(const float*gq,const float*tab,const int tq0,const bf16*Qw0,const bf16*__restrict__ Kl,const bf16*__restrict__ Vl,const int NT,bf16*Ow0,char*shm){
;     ...
;   int t=1;
;     ...
;   for(;t+5<NT;t+=2){
;     STEP(pB0,pB1,pA0,pA1,t,true,true,true);     WAIT_BAR(2); RESC(); ROT();
;     STEP(pA0,pA1,pB0,pB1,t+1,true,true,true);   WAIT_BAR(2); RESC(); ROT();
	v_add_f32_e32 v50, v50, v51
	v_add_f32_e32 v50, v50, v52
	ds_read_b64_tr_b16 v[52:53], v233 offset:40960
	ds_read_b64_tr_b16 v[54:55], v233 offset:41472
	v_add_f32_e32 v60, v82, v83
	v_add_f32_e32 v60, v84, v60
	v_add_f32_e32 v60, v85, v60
	v_add_f32_e32 v60, v86, v60
	v_add_f32_e32 v64, v87, v60
	v_cvt_pk_bf16_f32 v154, v82, v83
	v_cvt_pk_bf16_f32 v155, v84, v85
	s_waitcnt lgkmcnt(9)
	v_mfma_f32_32x32x16_bf16 v[114:129], v[190:193], v[158:161], v[2:17]
	ds_read_b64_tr_b16 v[60:61], v233 offset:45056
	ds_read_b64_tr_b16 v[62:63], v233 offset:45568
	v_add_f32_e32 v64, v88, v64
	v_add_f32_e32 v64, v89, v64
	v_add_f32_e32 v64, v90, v64
	v_add_f32_e32 v64, v91, v64
	v_cvt_pk_bf16_f32 v156, v86, v87
	v_cvt_pk_bf16_f32 v157, v88, v89
	s_waitcnt lgkmcnt(10)
	v_mfma_f32_32x32x16_bf16 v[98:113], v[186:189], v[158:161], v[2:17]
	ds_read_b64_tr_b16 v[82:83], v233 offset:41984
	ds_read_b64_tr_b16 v[84:85], v233 offset:42496
	v_add_f32_e32 v64, v92, v64
	v_add_f32_e32 v64, v93, v64
	v_add_f32_e32 v64, v94, v64
	v_add_f32_e32 v64, v95, v64
	v_cvt_pk_bf16_f32 v146, v90, v91
	v_cvt_pk_bf16_f32 v147, v92, v93
	s_waitcnt lgkmcnt(11)
	v_mfma_f32_32x32x16_bf16 v[114:129], v[182:185], v[150:153], v[114:129]
	ds_read_b64_tr_b16 v[86:87], v233 offset:46080
	ds_read_b64_tr_b16 v[88:89], v233 offset:46592
	v_add_f32_e32 v64, v96, v64
	v_add_f32_e32 v64, v97, v64
	v_add_f32_e32 v64, v66, v64
	v_add_f32_e32 v64, v67, v64
	v_cvt_pk_bf16_f32 v148, v94, v95
	v_cvt_pk_bf16_f32 v149, v96, v97
	s_waitcnt lgkmcnt(12)
	v_mfma_f32_32x32x16_bf16 v[98:113], v[178:181], v[150:153], v[98:113]
	ds_read_b64_tr_b16 v[90:91], v233 offset:43008
	ds_read_b64_tr_b16 v[92:93], v233 offset:43520
	v_add_f32_e32 v64, v68, v64
	v_add_f32_e32 v64, v69, v64
	v_add_f32_e32 v64, v70, v64
	v_add_f32_e32 v94, v71, v64
	v_cvt_pk_bf16_f32 v138, v66, v67
	v_cvt_pk_bf16_f32 v139, v68, v69
	s_waitcnt lgkmcnt(13)
	v_mfma_f32_32x32x16_bf16 v[114:129], v[174:177], v[142:145], v[114:129]
	ds_read_b64_tr_b16 v[64:65], v233 offset:47104
	ds_read_b64_tr_b16 v[66:67], v233 offset:47616
	v_add_f32_e32 v68, v72, v94
	v_add_f32_e32 v68, v73, v68
	v_add_f32_e32 v68, v74, v68
	v_add_f32_e32 v94, v75, v68
	v_cvt_pk_bf16_f32 v140, v70, v71
	v_cvt_pk_bf16_f32 v141, v72, v73
	s_waitcnt lgkmcnt(14)
	v_mfma_f32_32x32x16_bf16 v[98:113], v[170:173], v[142:145], v[98:113]
	ds_read_b64_tr_b16 v[68:69], v233 offset:44032
	ds_read_b64_tr_b16 v[70:71], v233 offset:44544
	v_add_f32_e32 v72, v76, v94
	v_add_f32_e32 v72, v77, v72
	v_add_f32_e32 v72, v78, v72
	v_add_f32_e32 v94, v79, v72
	v_cvt_pk_bf16_f32 v130, v74, v75
	v_cvt_pk_bf16_f32 v131, v76, v77
	s_waitcnt lgkmcnt(14)
	v_mfma_f32_32x32x16_bf16 v[114:129], v[166:169], v[134:137], v[114:129]
	ds_read_b64_tr_b16 v[72:73], v233 offset:48128
	ds_read_b64_tr_b16 v[74:75], v233 offset:48640
	v_add_f32_e32 v51, v80, v94
	v_add_f32_e32 v51, v81, v51
	v_cvt_pk_bf16_f32 v132, v78, v79
	v_cvt_pk_bf16_f32 v133, v80, v81
	v_mfma_f32_32x32x16_bf16 v[98:113], v[162:165], v[134:137], v[98:113]
	s_mov_b32 m0, s18
	s_nop 0
	global_load_lds_dwordx4 v240, s[100:101]
	s_add_i32 m0, s19, 0x2000
	s_nop 0
	global_load_lds_dwordx4 v241, s[100:101]
	s_waitcnt lgkmcnt(14)
	v_mfma_f32_32x32x16_bf16 v[18:33], v[154:157], v[52:55], v[18:33]
	s_add_u32 s100, s100, 0x2000
	s_addc_u32 s101, s101, 0
	v_exp_f32_e32 v114, v114
	v_exp_f32_e32 v115, v115
	v_exp_f32_e32 v116, v116
	v_exp_f32_e32 v117, v117
	s_waitcnt lgkmcnt(12)
	v_mfma_f32_32x32x16_bf16 v[34:49], v[154:157], v[60:63], v[34:49]
	v_exp_f32_e32 v118, v118
	v_exp_f32_e32 v119, v119
	v_exp_f32_e32 v120, v120
	v_exp_f32_e32 v121, v121
	ds_read_b128 v[60:63], v230 offset:8192
	ds_read_b128 v[162:165], v230 offset:8704
	s_waitcnt lgkmcnt(12)
	v_mfma_f32_32x32x16_bf16 v[18:33], v[146:149], v[82:85], v[18:33]
	v_exp_f32_e32 v122, v122
	v_exp_f32_e32 v123, v123
	v_exp_f32_e32 v124, v124
	v_exp_f32_e32 v125, v125
	ds_read_b128 v[166:169], v230 offset:10240
	ds_read_b128 v[170:173], v230 offset:10752
	s_waitcnt lgkmcnt(12)
	v_mfma_f32_32x32x16_bf16 v[34:49], v[146:149], v[86:89], v[34:49]
	v_exp_f32_e32 v126, v126
	v_exp_f32_e32 v127, v127
	v_exp_f32_e32 v128, v128
	v_exp_f32_e32 v129, v129
	ds_read_b128 v[174:177], v230 offset:12288
	ds_read_b128 v[178:181], v230 offset:12800
	s_waitcnt lgkmcnt(12)
	v_mfma_f32_32x32x16_bf16 v[18:33], v[138:141], v[90:93], v[18:33]
	v_exp_f32_e32 v98, v98
	v_exp_f32_e32 v99, v99
	v_exp_f32_e32 v100, v100
	v_exp_f32_e32 v101, v101
	ds_read_b128 v[182:185], v230 offset:14336
	ds_read_b128 v[52:55], v230 offset:14848
	s_waitcnt lgkmcnt(12)
	v_mfma_f32_32x32x16_bf16 v[34:49], v[138:141], v[64:67], v[34:49]
	v_exp_f32_e32 v102, v102
	v_exp_f32_e32 v103, v103
	v_exp_f32_e32 v104, v104
	v_exp_f32_e32 v105, v105
	s_waitcnt lgkmcnt(10)
	v_mfma_f32_32x32x16_bf16 v[18:33], v[130:133], v[68:71], v[18:33]
	v_exp_f32_e32 v106, v106
	v_exp_f32_e32 v107, v107
	v_exp_f32_e32 v108, v108
	v_exp_f32_e32 v109, v109
	s_waitcnt lgkmcnt(8)
	v_mfma_f32_32x32x16_bf16 v[34:49], v[130:133], v[72:75], v[34:49]
	v_exp_f32_e32 v110, v110
	v_exp_f32_e32 v111, v111
	v_exp_f32_e32 v112, v112
	v_exp_f32_e32 v113, v113
	s_waitcnt vmcnt(2) lgkmcnt(0)
	s_barrier
; #define WAIT_BAR(N) asm volatile("s_waitcnt vmcnt(" #N ") lgkmcnt(0)\n\ts_barrier":::"memory")
;   #define RESC() do{ if(resc){ asm volatile("s_waitcnt lgkmcnt(0)":::"memory"); \
;       _Pragma("unroll") for(int d_=0;d_<2;++d_) _Pragma("unroll") for(int r=0;r<16;++r)o[d_][r]*=wsf[crow(r,hi)]; } }while(0)
;   #define ROT() do{sl_prev=sl_cur;sl_cur=sl_next;sl_next=(sl_next==(NSLOT-1)*SLOTB)?0:sl_next+SLOTB;}while(0)
; template<int THRL,bool FIXREF> __device__ __forceinline__ void attn_unit(const float*gq,const float*tab,const int tq0,const bf16*Qw0,const bf16*__restrict__ Kl,const bf16*__restrict__ Vl,const int NT,bf16*Ow0,char*shm){
;     ...
;   int t=1;
;     ...
;   for(;t+5<NT;t+=2){
;     STEP(pB0,pB1,pA0,pA1,t,true,true,true);     WAIT_BAR(2); RESC(); ROT();
;     STEP(pA0,pA1,pB0,pB1,t+1,true,true,true);   WAIT_BAR(2); RESC(); ROT();
	ds_read_b64_tr_b16 v[186:187], v233 offset:24576
	ds_read_b64_tr_b16 v[188:189], v233 offset:25088
	s_waitcnt lgkmcnt(9)
	v_mfma_f32_32x32x16_bf16 v[82:97], v[60:63], v[158:161], v[2:17]
	v_add_f32_e32 v65, v114, v115
	v_add_f32_e32 v65, v116, v65
	v_add_f32_e32 v65, v117, v65
	v_add_f32_e32 v65, v118, v65
	v_add_f32_e32 v65, v119, v65
	v_cvt_pk_bf16_f32 v154, v114, v115
	v_cvt_pk_bf16_f32 v155, v116, v117
	ds_read_b64_tr_b16 v[60:61], v233 offset:28672
	ds_read_b64_tr_b16 v[62:63], v233 offset:29184
	s_waitcnt lgkmcnt(10)
	v_mfma_f32_32x32x16_bf16 v[66:81], v[162:165], v[158:161], v[2:17]
	v_add_f32_e32 v65, v120, v65
	v_add_f32_e32 v65, v121, v65
	v_add_f32_e32 v65, v122, v65
	v_add_f32_e32 v65, v123, v65
	v_cvt_pk_bf16_f32 v156, v118, v119
	v_cvt_pk_bf16_f32 v157, v120, v121
	ds_read_b64_tr_b16 v[114:115], v233 offset:25600
	ds_read_b64_tr_b16 v[116:117], v233 offset:26112
	s_waitcnt lgkmcnt(11)
	v_mfma_f32_32x32x16_bf16 v[82:97], v[166:169], v[150:153], v[82:97]
	v_add_f32_e32 v65, v124, v65
	v_add_f32_e32 v65, v125, v65
	v_add_f32_e32 v65, v126, v65
	v_add_f32_e32 v65, v127, v65
	v_cvt_pk_bf16_f32 v146, v122, v123
	v_cvt_pk_bf16_f32 v147, v124, v125
	ds_read_b64_tr_b16 v[118:119], v233 offset:29696
	ds_read_b64_tr_b16 v[120:121], v233 offset:30208
	s_waitcnt lgkmcnt(12)
	v_mfma_f32_32x32x16_bf16 v[66:81], v[170:173], v[150:153], v[66:81]
	v_add_f32_e32 v65, v128, v65
	v_add_f32_e32 v65, v129, v65
	v_add_f32_e32 v65, v98, v65
	v_add_f32_e32 v65, v99, v65
	v_cvt_pk_bf16_f32 v148, v126, v127
	v_cvt_pk_bf16_f32 v149, v128, v129
	ds_read_b64_tr_b16 v[122:123], v233 offset:26624
	ds_read_b64_tr_b16 v[124:125], v233 offset:27136
	s_waitcnt lgkmcnt(13)
	v_mfma_f32_32x32x16_bf16 v[82:97], v[174:177], v[142:145], v[82:97]
	v_add_f32_e32 v65, v100, v65
	v_add_f32_e32 v65, v101, v65
	v_add_f32_e32 v65, v102, v65
	v_add_f32_e32 v65, v103, v65
	v_cvt_pk_bf16_f32 v138, v98, v99
	v_cvt_pk_bf16_f32 v139, v100, v101
	ds_read_b64_tr_b16 v[98:99], v233 offset:30720
	ds_read_b64_tr_b16 v[100:101], v233 offset:31232
	s_waitcnt lgkmcnt(14)
	v_mfma_f32_32x32x16_bf16 v[66:81], v[178:181], v[142:145], v[66:81]
	v_add_f32_e32 v65, v104, v65
	v_add_f32_e32 v65, v105, v65
	v_add_f32_e32 v65, v106, v65
	v_add_f32_e32 v65, v107, v65
	v_cvt_pk_bf16_f32 v140, v102, v103
	v_cvt_pk_bf16_f32 v141, v104, v105
	ds_read_b64_tr_b16 v[102:103], v233 offset:27648
	ds_read_b64_tr_b16 v[104:105], v233 offset:28160
	s_waitcnt lgkmcnt(14)
	v_mfma_f32_32x32x16_bf16 v[82:97], v[182:185], v[134:137], v[82:97]
	v_add_f32_e32 v65, v108, v65
	v_add_f32_e32 v65, v109, v65
	v_add_f32_e32 v65, v110, v65
	v_add_f32_e32 v65, v111, v65
	v_cvt_pk_bf16_f32 v130, v106, v107
	v_cvt_pk_bf16_f32 v131, v108, v109
	ds_read_b64_tr_b16 v[106:107], v233 offset:31744
	ds_read_b64_tr_b16 v[108:109], v233 offset:32256
	v_mfma_f32_32x32x16_bf16 v[66:81], v[52:55], v[134:137], v[66:81]
	v_add_f32_e32 v52, v112, v65
	v_add_f32_e32 v52, v113, v52
	v_cvt_pk_bf16_f32 v132, v110, v111
	v_cvt_pk_bf16_f32 v133, v112, v113
	s_add_i32 m0, s18, 0x2000
	s_nop 0
	global_load_lds_dwordx4 v240, s[100:101]
	s_add_i32 m0, s19, 0x4000
	s_nop 0
	global_load_lds_dwordx4 v241, s[100:101]
	s_waitcnt lgkmcnt(14)
	v_mfma_f32_32x32x16_bf16 v[18:33], v[154:157], v[186:189], v[18:33]
	s_add_u32 s100, s100, 0x2000
	s_addc_u32 s101, s101, 0
	v_exp_f32_e32 v82, v82
	v_exp_f32_e32 v83, v83
	v_exp_f32_e32 v84, v84
	v_exp_f32_e32 v85, v85
	s_waitcnt lgkmcnt(12)
	v_mfma_f32_32x32x16_bf16 v[34:49], v[154:157], v[60:63], v[34:49]
	v_exp_f32_e32 v86, v86
	v_exp_f32_e32 v87, v87
	v_exp_f32_e32 v88, v88
	v_exp_f32_e32 v89, v89
	ds_read_b128 v[190:193], v230 offset:16384
	ds_read_b128 v[186:189], v230 offset:16896
	s_waitcnt lgkmcnt(12)
	v_mfma_f32_32x32x16_bf16 v[18:33], v[146:149], v[114:117], v[18:33]
	v_exp_f32_e32 v90, v90
	v_exp_f32_e32 v91, v91
	v_exp_f32_e32 v92, v92
	v_exp_f32_e32 v93, v93
	ds_read_b128 v[182:185], v230 offset:18432
	ds_read_b128 v[178:181], v230 offset:18944
	s_waitcnt lgkmcnt(12)
	v_mfma_f32_32x32x16_bf16 v[34:49], v[146:149], v[118:121], v[34:49]
	v_exp_f32_e32 v94, v94
	v_exp_f32_e32 v95, v95
	v_exp_f32_e32 v96, v96
	v_exp_f32_e32 v97, v97
	ds_read_b128 v[174:177], v230 offset:20480
	ds_read_b128 v[170:173], v230 offset:20992
	s_waitcnt lgkmcnt(12)
	v_mfma_f32_32x32x16_bf16 v[18:33], v[138:141], v[122:125], v[18:33]
	v_exp_f32_e32 v66, v66
	v_exp_f32_e32 v67, v67
	v_exp_f32_e32 v68, v68
	v_exp_f32_e32 v69, v69
	ds_read_b128 v[166:169], v230 offset:22528
	ds_read_b128 v[162:165], v230 offset:23040
	s_waitcnt lgkmcnt(12)
	v_mfma_f32_32x32x16_bf16 v[34:49], v[138:141], v[98:101], v[34:49]
	v_exp_f32_e32 v70, v70
	v_exp_f32_e32 v71, v71
	v_exp_f32_e32 v72, v72
	v_exp_f32_e32 v73, v73
	s_waitcnt lgkmcnt(10)
	v_mfma_f32_32x32x16_bf16 v[18:33], v[130:133], v[102:105], v[18:33]
	v_exp_f32_e32 v74, v74
	v_exp_f32_e32 v75, v75
	v_exp_f32_e32 v76, v76
	v_exp_f32_e32 v77, v77
	s_waitcnt lgkmcnt(8)
	v_mfma_f32_32x32x16_bf16 v[34:49], v[130:133], v[106:109], v[34:49]
	v_exp_f32_e32 v78, v78
	v_exp_f32_e32 v79, v79
	v_exp_f32_e32 v80, v80
	v_exp_f32_e32 v81, v81
	s_waitcnt vmcnt(2) lgkmcnt(0)
	s_barrier
; #define WAIT_BAR(N) asm volatile("s_waitcnt vmcnt(" #N ") lgkmcnt(0)\n\ts_barrier":::"memory")
;   #define RESC() do{ if(resc){ asm volatile("s_waitcnt lgkmcnt(0)":::"memory"); \
;       _Pragma("unroll") for(int d_=0;d_<2;++d_) _Pragma("unroll") for(int r=0;r<16;++r)o[d_][r]*=wsf[crow(r,hi)]; } }while(0)
;   #define ROT() do{sl_prev=sl_cur;sl_cur=sl_next;sl_next=(sl_next==(NSLOT-1)*SLOTB)?0:sl_next+SLOTB;}while(0)
; template<int THRL,bool FIXREF> __device__ __forceinline__ void attn_unit(const float*gq,const float*tab,const int tq0,const bf16*Qw0,const bf16*__restrict__ Kl,const bf16*__restrict__ Vl,const int NT,bf16*Ow0,char*shm){
;     ...
;   int t=1;
;     ...
;   for(;t+5<NT;t+=2){
;     STEP(pB0,pB1,pA0,pA1,t,true,true,true);     WAIT_BAR(2); RESC(); ROT();
;     STEP(pA0,pA1,pB0,pB1,t+1,true,true,true);   WAIT_BAR(2); RESC(); ROT();
	v_add_f32_e32 v50, v50, v51
	v_add_f32_e32 v50, v50, v52
	ds_read_b64_tr_b16 v[52:53], v233 offset:32768
	ds_read_b64_tr_b16 v[54:55], v233 offset:33280
	v_add_f32_e32 v60, v82, v83
	v_add_f32_e32 v60, v84, v60
	v_add_f32_e32 v60, v85, v60
	v_add_f32_e32 v60, v86, v60
	v_add_f32_e32 v64, v87, v60
	v_cvt_pk_bf16_f32 v154, v82, v83
	v_cvt_pk_bf16_f32 v155, v84, v85
	s_waitcnt lgkmcnt(9)
	v_mfma_f32_32x32x16_bf16 v[114:129], v[190:193], v[158:161], v[2:17]
	ds_read_b64_tr_b16 v[60:61], v233 offset:36864
	ds_read_b64_tr_b16 v[62:63], v233 offset:37376
	v_add_f32_e32 v64, v88, v64
	v_add_f32_e32 v64, v89, v64
	v_add_f32_e32 v64, v90, v64
	v_add_f32_e32 v64, v91, v64
	v_cvt_pk_bf16_f32 v156, v86, v87
	v_cvt_pk_bf16_f32 v157, v88, v89
	s_waitcnt lgkmcnt(10)
	v_mfma_f32_32x32x16_bf16 v[98:113], v[186:189], v[158:161], v[2:17]
	ds_read_b64_tr_b16 v[82:83], v233 offset:33792
	ds_read_b64_tr_b16 v[84:85], v233 offset:34304
	v_add_f32_e32 v64, v92, v64
	v_add_f32_e32 v64, v93, v64
	v_add_f32_e32 v64, v94, v64
	v_add_f32_e32 v64, v95, v64
	v_cvt_pk_bf16_f32 v146, v90, v91
	v_cvt_pk_bf16_f32 v147, v92, v93
	s_waitcnt lgkmcnt(11)
	v_mfma_f32_32x32x16_bf16 v[114:129], v[182:185], v[150:153], v[114:129]
	ds_read_b64_tr_b16 v[86:87], v233 offset:37888
	ds_read_b64_tr_b16 v[88:89], v233 offset:38400
	v_add_f32_e32 v64, v96, v64
	v_add_f32_e32 v64, v97, v64
	v_add_f32_e32 v64, v66, v64
	v_add_f32_e32 v64, v67, v64
	v_cvt_pk_bf16_f32 v148, v94, v95
	v_cvt_pk_bf16_f32 v149, v96, v97
	s_waitcnt lgkmcnt(12)
	v_mfma_f32_32x32x16_bf16 v[98:113], v[178:181], v[150:153], v[98:113]
	ds_read_b64_tr_b16 v[90:91], v233 offset:34816
	ds_read_b64_tr_b16 v[92:93], v233 offset:35328
	v_add_f32_e32 v64, v68, v64
	v_add_f32_e32 v64, v69, v64
	v_add_f32_e32 v64, v70, v64
	v_add_f32_e32 v94, v71, v64
	v_cvt_pk_bf16_f32 v138, v66, v67
	v_cvt_pk_bf16_f32 v139, v68, v69
	s_waitcnt lgkmcnt(13)
	v_mfma_f32_32x32x16_bf16 v[114:129], v[174:177], v[142:145], v[114:129]
	ds_read_b64_tr_b16 v[64:65], v233 offset:38912
	ds_read_b64_tr_b16 v[66:67], v233 offset:39424
	v_add_f32_e32 v68, v72, v94
	v_add_f32_e32 v68, v73, v68
	v_add_f32_e32 v68, v74, v68
	v_add_f32_e32 v94, v75, v68
	v_cvt_pk_bf16_f32 v140, v70, v71
	v_cvt_pk_bf16_f32 v141, v72, v73
	s_waitcnt lgkmcnt(14)
	v_mfma_f32_32x32x16_bf16 v[98:113], v[170:173], v[142:145], v[98:113]
	ds_read_b64_tr_b16 v[68:69], v233 offset:35840
	ds_read_b64_tr_b16 v[70:71], v233 offset:36352
	v_add_f32_e32 v72, v76, v94
	v_add_f32_e32 v72, v77, v72
	v_add_f32_e32 v72, v78, v72
	v_add_f32_e32 v94, v79, v72
	v_cvt_pk_bf16_f32 v130, v74, v75
	v_cvt_pk_bf16_f32 v131, v76, v77
	s_waitcnt lgkmcnt(14)
	v_mfma_f32_32x32x16_bf16 v[114:129], v[166:169], v[134:137], v[114:129]
	ds_read_b64_tr_b16 v[72:73], v233 offset:39936
	ds_read_b64_tr_b16 v[74:75], v233 offset:40448
	v_add_f32_e32 v51, v80, v94
	v_add_f32_e32 v51, v81, v51
	v_cvt_pk_bf16_f32 v132, v78, v79
	v_cvt_pk_bf16_f32 v133, v80, v81
	v_mfma_f32_32x32x16_bf16 v[98:113], v[162:165], v[134:137], v[98:113]
	s_add_i32 m0, s18, 0x4000
	s_nop 0
	global_load_lds_dwordx4 v240, s[100:101]
	s_mov_b32 m0, s19
	s_nop 0
	global_load_lds_dwordx4 v241, s[100:101]
	s_waitcnt lgkmcnt(14)
	v_mfma_f32_32x32x16_bf16 v[18:33], v[154:157], v[52:55], v[18:33]
	s_add_u32 s100, s100, 0x2000
	s_addc_u32 s101, s101, 0
	v_exp_f32_e32 v114, v114
	v_exp_f32_e32 v115, v115
	v_exp_f32_e32 v116, v116
	v_exp_f32_e32 v117, v117
	s_waitcnt lgkmcnt(12)
	v_mfma_f32_32x32x16_bf16 v[34:49], v[154:157], v[60:63], v[34:49]
	v_exp_f32_e32 v118, v118
	v_exp_f32_e32 v119, v119
	v_exp_f32_e32 v120, v120
	v_exp_f32_e32 v121, v121
	ds_read_b128 v[60:63], v230
	ds_read_b128 v[162:165], v230 offset:512
	s_waitcnt lgkmcnt(12)
	v_mfma_f32_32x32x16_bf16 v[18:33], v[146:149], v[82:85], v[18:33]
	v_exp_f32_e32 v122, v122
	v_exp_f32_e32 v123, v123
	v_exp_f32_e32 v124, v124
	v_exp_f32_e32 v125, v125
	ds_read_b128 v[166:169], v230 offset:2048
	ds_read_b128 v[170:173], v230 offset:2560
	s_waitcnt lgkmcnt(12)
	v_mfma_f32_32x32x16_bf16 v[34:49], v[146:149], v[86:89], v[34:49]
	v_exp_f32_e32 v126, v126
	v_exp_f32_e32 v127, v127
	v_exp_f32_e32 v128, v128
	v_exp_f32_e32 v129, v129
	ds_read_b128 v[174:177], v230 offset:4096
	ds_read_b128 v[178:181], v230 offset:4608
	s_waitcnt lgkmcnt(12)
	v_mfma_f32_32x32x16_bf16 v[18:33], v[138:141], v[90:93], v[18:33]
	v_exp_f32_e32 v98, v98
	v_exp_f32_e32 v99, v99
	v_exp_f32_e32 v100, v100
	v_exp_f32_e32 v101, v101
	ds_read_b128 v[182:185], v230 offset:6144
	ds_read_b128 v[52:55], v230 offset:6656
	s_waitcnt lgkmcnt(12)
	v_mfma_f32_32x32x16_bf16 v[34:49], v[138:141], v[64:67], v[34:49]
	v_exp_f32_e32 v102, v102
	v_exp_f32_e32 v103, v103
	v_exp_f32_e32 v104, v104
	v_exp_f32_e32 v105, v105
	s_waitcnt lgkmcnt(10)
	v_mfma_f32_32x32x16_bf16 v[18:33], v[130:133], v[68:71], v[18:33]
	v_exp_f32_e32 v106, v106
	v_exp_f32_e32 v107, v107
	v_exp_f32_e32 v108, v108
	v_exp_f32_e32 v109, v109
	s_waitcnt lgkmcnt(8)
	v_mfma_f32_32x32x16_bf16 v[34:49], v[130:133], v[72:75], v[34:49]
	v_exp_f32_e32 v110, v110
	v_exp_f32_e32 v111, v111
	v_exp_f32_e32 v112, v112
	v_exp_f32_e32 v113, v113
	s_waitcnt vmcnt(2) lgkmcnt(0)
	s_barrier
; #define WAIT_BAR(N) asm volatile("s_waitcnt vmcnt(" #N ") lgkmcnt(0)\n\ts_barrier":::"memory")
;   #define RESC() do{ if(resc){ asm volatile("s_waitcnt lgkmcnt(0)":::"memory"); \
;       _Pragma("unroll") for(int d_=0;d_<2;++d_) _Pragma("unroll") for(int r=0;r<16;++r)o[d_][r]*=wsf[crow(r,hi)]; } }while(0)
;   #define ROT() do{sl_prev=sl_cur;sl_cur=sl_next;sl_next=(sl_next==(NSLOT-1)*SLOTB)?0:sl_next+SLOTB;}while(0)
; template<int THRL,bool FIXREF> __device__ __forceinline__ void attn_unit(const float*gq,const float*tab,const int tq0,const bf16*Qw0,const bf16*__restrict__ Kl,const bf16*__restrict__ Vl,const int NT,bf16*Ow0,char*shm){
;     ...
;   int t=1;
;     ...
;   for(;t+5<NT;t+=2){
;     STEP(pB0,pB1,pA0,pA1,t,true,true,true);     WAIT_BAR(2); RESC(); ROT();
;     STEP(pA0,pA1,pB0,pB1,t+1,true,true,true);   WAIT_BAR(2); RESC(); ROT();
	ds_read_b64_tr_b16 v[186:187], v233 offset:40960
	ds_read_b64_tr_b16 v[188:189], v233 offset:41472
	s_waitcnt lgkmcnt(9)
	v_mfma_f32_32x32x16_bf16 v[82:97], v[60:63], v[158:161], v[2:17]
	v_add_f32_e32 v65, v114, v115
	v_add_f32_e32 v65, v116, v65
	v_add_f32_e32 v65, v117, v65
	v_add_f32_e32 v65, v118, v65
	v_add_f32_e32 v65, v119, v65
	v_cvt_pk_bf16_f32 v154, v114, v115
	v_cvt_pk_bf16_f32 v155, v116, v117
	ds_read_b64_tr_b16 v[60:61], v233 offset:45056
	ds_read_b64_tr_b16 v[62:63], v233 offset:45568
	s_waitcnt lgkmcnt(10)
	v_mfma_f32_32x32x16_bf16 v[66:81], v[162:165], v[158:161], v[2:17]
	v_add_f32_e32 v65, v120, v65
	v_add_f32_e32 v65, v121, v65
	v_add_f32_e32 v65, v122, v65
	v_add_f32_e32 v65, v123, v65
	v_cvt_pk_bf16_f32 v156, v118, v119
	v_cvt_pk_bf16_f32 v157, v120, v121
	ds_read_b64_tr_b16 v[114:115], v233 offset:41984
	ds_read_b64_tr_b16 v[116:117], v233 offset:42496
	s_waitcnt lgkmcnt(11)
	v_mfma_f32_32x32x16_bf16 v[82:97], v[166:169], v[150:153], v[82:97]
	v_add_f32_e32 v65, v124, v65
	v_add_f32_e32 v65, v125, v65
	v_add_f32_e32 v65, v126, v65
	v_add_f32_e32 v65, v127, v65
	v_cvt_pk_bf16_f32 v146, v122, v123
	v_cvt_pk_bf16_f32 v147, v124, v125
	ds_read_b64_tr_b16 v[118:119], v233 offset:46080
	ds_read_b64_tr_b16 v[120:121], v233 offset:46592
	s_waitcnt lgkmcnt(12)
	v_mfma_f32_32x32x16_bf16 v[66:81], v[170:173], v[150:153], v[66:81]
	v_add_f32_e32 v65, v128, v65
	v_add_f32_e32 v65, v129, v65
	v_add_f32_e32 v65, v98, v65
	v_add_f32_e32 v65, v99, v65
	v_cvt_pk_bf16_f32 v148, v126, v127
	v_cvt_pk_bf16_f32 v149, v128, v129
	ds_read_b64_tr_b16 v[122:123], v233 offset:43008
	ds_read_b64_tr_b16 v[124:125], v233 offset:43520
	s_waitcnt lgkmcnt(13)
	v_mfma_f32_32x32x16_bf16 v[82:97], v[174:177], v[142:145], v[82:97]
	v_add_f32_e32 v65, v100, v65
	v_add_f32_e32 v65, v101, v65
	v_add_f32_e32 v65, v102, v65
	v_add_f32_e32 v65, v103, v65
	v_cvt_pk_bf16_f32 v138, v98, v99
	v_cvt_pk_bf16_f32 v139, v100, v101
	ds_read_b64_tr_b16 v[98:99], v233 offset:47104
	ds_read_b64_tr_b16 v[100:101], v233 offset:47616
	s_waitcnt lgkmcnt(14)
	v_mfma_f32_32x32x16_bf16 v[66:81], v[178:181], v[142:145], v[66:81]
	v_add_f32_e32 v65, v104, v65
	v_add_f32_e32 v65, v105, v65
	v_add_f32_e32 v65, v106, v65
	v_add_f32_e32 v65, v107, v65
	v_cvt_pk_bf16_f32 v140, v102, v103
	v_cvt_pk_bf16_f32 v141, v104, v105
	ds_read_b64_tr_b16 v[102:103], v233 offset:44032
	ds_read_b64_tr_b16 v[104:105], v233 offset:44544
	s_waitcnt lgkmcnt(14)
	v_mfma_f32_32x32x16_bf16 v[82:97], v[182:185], v[134:137], v[82:97]
	v_add_f32_e32 v65, v108, v65
	v_add_f32_e32 v65, v109, v65
	v_add_f32_e32 v65, v110, v65
	v_add_f32_e32 v65, v111, v65
	v_cvt_pk_bf16_f32 v130, v106, v107
	v_cvt_pk_bf16_f32 v131, v108, v109
	ds_read_b64_tr_b16 v[106:107], v233 offset:48128
	ds_read_b64_tr_b16 v[108:109], v233 offset:48640
	v_mfma_f32_32x32x16_bf16 v[66:81], v[52:55], v[134:137], v[66:81]
	v_add_f32_e32 v52, v112, v65
	v_add_f32_e32 v52, v113, v52
	v_cvt_pk_bf16_f32 v132, v110, v111
	v_cvt_pk_bf16_f32 v133, v112, v113
	s_mov_b32 m0, s18
	s_nop 0
	global_load_lds_dwordx4 v240, s[100:101]
	s_add_i32 m0, s19, 0x2000
	s_nop 0
	global_load_lds_dwordx4 v241, s[100:101]
	s_waitcnt lgkmcnt(14)
	v_mfma_f32_32x32x16_bf16 v[18:33], v[154:157], v[186:189], v[18:33]
	s_add_u32 s100, s100, 0x2000
	s_addc_u32 s101, s101, 0
	v_exp_f32_e32 v82, v82
	v_exp_f32_e32 v83, v83
	v_exp_f32_e32 v84, v84
	v_exp_f32_e32 v85, v85
	s_waitcnt lgkmcnt(12)
	v_mfma_f32_32x32x16_bf16 v[34:49], v[154:157], v[60:63], v[34:49]
	v_exp_f32_e32 v86, v86
	v_exp_f32_e32 v87, v87
	v_exp_f32_e32 v88, v88
	v_exp_f32_e32 v89, v89
	ds_read_b128 v[190:193], v230 offset:8192
	ds_read_b128 v[186:189], v230 offset:8704
	s_waitcnt lgkmcnt(12)
	v_mfma_f32_32x32x16_bf16 v[18:33], v[146:149], v[114:117], v[18:33]
	v_exp_f32_e32 v90, v90
	v_exp_f32_e32 v91, v91
	v_exp_f32_e32 v92, v92
	v_exp_f32_e32 v93, v93
	ds_read_b128 v[182:185], v230 offset:10240
	ds_read_b128 v[178:181], v230 offset:10752
	s_waitcnt lgkmcnt(12)
	v_mfma_f32_32x32x16_bf16 v[34:49], v[146:149], v[118:121], v[34:49]
	v_exp_f32_e32 v94, v94
	v_exp_f32_e32 v95, v95
	v_exp_f32_e32 v96, v96
	v_exp_f32_e32 v97, v97
	ds_read_b128 v[174:177], v230 offset:12288
	ds_read_b128 v[170:173], v230 offset:12800
	s_waitcnt lgkmcnt(12)
	v_mfma_f32_32x32x16_bf16 v[18:33], v[138:141], v[122:125], v[18:33]
	v_exp_f32_e32 v66, v66
	v_exp_f32_e32 v67, v67
	v_exp_f32_e32 v68, v68
	v_exp_f32_e32 v69, v69
	ds_read_b128 v[166:169], v230 offset:14336
	ds_read_b128 v[162:165], v230 offset:14848
	s_waitcnt lgkmcnt(12)
	v_mfma_f32_32x32x16_bf16 v[34:49], v[138:141], v[98:101], v[34:49]
	v_exp_f32_e32 v70, v70
	v_exp_f32_e32 v71, v71
	v_exp_f32_e32 v72, v72
	v_exp_f32_e32 v73, v73
	s_waitcnt lgkmcnt(10)
	v_mfma_f32_32x32x16_bf16 v[18:33], v[130:133], v[102:105], v[18:33]
	v_exp_f32_e32 v74, v74
	v_exp_f32_e32 v75, v75
	v_exp_f32_e32 v76, v76
	v_exp_f32_e32 v77, v77
	s_waitcnt lgkmcnt(8)
	v_mfma_f32_32x32x16_bf16 v[34:49], v[130:133], v[106:109], v[34:49]
	v_exp_f32_e32 v78, v78
	v_exp_f32_e32 v79, v79
	v_exp_f32_e32 v80, v80
	v_exp_f32_e32 v81, v81
	s_waitcnt vmcnt(2) lgkmcnt(0)
	s_barrier
; #define WAIT_BAR(N) asm volatile("s_waitcnt vmcnt(" #N ") lgkmcnt(0)\n\ts_barrier":::"memory")
;   #define RESC() do{ if(resc){ asm volatile("s_waitcnt lgkmcnt(0)":::"memory"); \
;       _Pragma("unroll") for(int d_=0;d_<2;++d_) _Pragma("unroll") for(int r=0;r<16;++r)o[d_][r]*=wsf[crow(r,hi)]; } }while(0)
;   #define ROT() do{sl_prev=sl_cur;sl_cur=sl_next;sl_next=(sl_next==(NSLOT-1)*SLOTB)?0:sl_next+SLOTB;}while(0)
; template<int THRL,bool FIXREF> __device__ __forceinline__ void attn_unit(const float*gq,const float*tab,const int tq0,const bf16*Qw0,const bf16*__restrict__ Kl,const bf16*__restrict__ Vl,const int NT,bf16*Ow0,char*shm){
;     ...
;   int t=1;
;     ...
;   for(;t+5<NT;t+=2){
;     STEP(pB0,pB1,pA0,pA1,t,true,true,true);     WAIT_BAR(2); RESC(); ROT();
;     STEP(pA0,pA1,pB0,pB1,t+1,true,true,true);   WAIT_BAR(2); RESC(); ROT();
	v_add_f32_e32 v50, v50, v51
	v_add_f32_e32 v50, v50, v52
	ds_read_b64_tr_b16 v[52:53], v233 offset:24576
	ds_read_b64_tr_b16 v[54:55], v233 offset:25088
	v_add_f32_e32 v60, v82, v83
	v_add_f32_e32 v60, v84, v60
	v_add_f32_e32 v60, v85, v60
	v_add_f32_e32 v60, v86, v60
	v_add_f32_e32 v64, v87, v60
	v_cvt_pk_bf16_f32 v154, v82, v83
	v_cvt_pk_bf16_f32 v155, v84, v85
	s_waitcnt lgkmcnt(9)
	v_mfma_f32_32x32x16_bf16 v[114:129], v[190:193], v[158:161], v[2:17]
	ds_read_b64_tr_b16 v[60:61], v233 offset:28672
	ds_read_b64_tr_b16 v[62:63], v233 offset:29184
	v_add_f32_e32 v64, v88, v64
	v_add_f32_e32 v64, v89, v64
	v_add_f32_e32 v64, v90, v64
	v_add_f32_e32 v64, v91, v64
	v_cvt_pk_bf16_f32 v156, v86, v87
	v_cvt_pk_bf16_f32 v157, v88, v89
	s_waitcnt lgkmcnt(10)
	v_mfma_f32_32x32x16_bf16 v[98:113], v[186:189], v[158:161], v[2:17]
	ds_read_b64_tr_b16 v[82:83], v233 offset:25600
	ds_read_b64_tr_b16 v[84:85], v233 offset:26112
	v_add_f32_e32 v64, v92, v64
	v_add_f32_e32 v64, v93, v64
	v_add_f32_e32 v64, v94, v64
	v_add_f32_e32 v64, v95, v64
	v_cvt_pk_bf16_f32 v146, v90, v91
	v_cvt_pk_bf16_f32 v147, v92, v93
	s_waitcnt lgkmcnt(11)
	v_mfma_f32_32x32x16_bf16 v[114:129], v[182:185], v[150:153], v[114:129]
	ds_read_b64_tr_b16 v[86:87], v233 offset:29696
	ds_read_b64_tr_b16 v[88:89], v233 offset:30208
	v_add_f32_e32 v64, v96, v64
	v_add_f32_e32 v64, v97, v64
	v_add_f32_e32 v64, v66, v64
	v_add_f32_e32 v64, v67, v64
	v_cvt_pk_bf16_f32 v148, v94, v95
	v_cvt_pk_bf16_f32 v149, v96, v97
	s_waitcnt lgkmcnt(12)
	v_mfma_f32_32x32x16_bf16 v[98:113], v[178:181], v[150:153], v[98:113]
	ds_read_b64_tr_b16 v[90:91], v233 offset:26624
	ds_read_b64_tr_b16 v[92:93], v233 offset:27136
	v_add_f32_e32 v64, v68, v64
	v_add_f32_e32 v64, v69, v64
	v_add_f32_e32 v64, v70, v64
	v_add_f32_e32 v94, v71, v64
	v_cvt_pk_bf16_f32 v138, v66, v67
	v_cvt_pk_bf16_f32 v139, v68, v69
	s_waitcnt lgkmcnt(13)
	v_mfma_f32_32x32x16_bf16 v[114:129], v[174:177], v[142:145], v[114:129]
	ds_read_b64_tr_b16 v[64:65], v233 offset:30720
	ds_read_b64_tr_b16 v[66:67], v233 offset:31232
	v_add_f32_e32 v68, v72, v94
	v_add_f32_e32 v68, v73, v68
	v_add_f32_e32 v68, v74, v68
	v_add_f32_e32 v94, v75, v68
	v_cvt_pk_bf16_f32 v140, v70, v71
	v_cvt_pk_bf16_f32 v141, v72, v73
	s_waitcnt lgkmcnt(14)
	v_mfma_f32_32x32x16_bf16 v[98:113], v[170:173], v[142:145], v[98:113]
	ds_read_b64_tr_b16 v[68:69], v233 offset:27648
	ds_read_b64_tr_b16 v[70:71], v233 offset:28160
	v_add_f32_e32 v72, v76, v94
	v_add_f32_e32 v72, v77, v72
	v_add_f32_e32 v72, v78, v72
	v_add_f32_e32 v94, v79, v72
	v_cvt_pk_bf16_f32 v130, v74, v75
	v_cvt_pk_bf16_f32 v131, v76, v77
	s_waitcnt lgkmcnt(14)
	v_mfma_f32_32x32x16_bf16 v[114:129], v[166:169], v[134:137], v[114:129]
	ds_read_b64_tr_b16 v[72:73], v233 offset:31744
	ds_read_b64_tr_b16 v[74:75], v233 offset:32256
	v_add_f32_e32 v51, v80, v94
	v_add_f32_e32 v51, v81, v51
	v_cvt_pk_bf16_f32 v132, v78, v79
	v_cvt_pk_bf16_f32 v133, v80, v81
	v_mfma_f32_32x32x16_bf16 v[98:113], v[162:165], v[134:137], v[98:113]
	s_add_i32 m0, s18, 0x2000
	s_nop 0
	global_load_lds_dwordx4 v240, s[100:101]
	s_add_i32 m0, s19, 0x4000
	s_nop 0
	global_load_lds_dwordx4 v241, s[100:101]
	s_waitcnt lgkmcnt(14)
	v_mfma_f32_32x32x16_bf16 v[18:33], v[154:157], v[52:55], v[18:33]
	s_add_u32 s100, s100, 0x2000
	s_addc_u32 s101, s101, 0
	v_exp_f32_e32 v114, v114
	v_exp_f32_e32 v115, v115
	v_exp_f32_e32 v116, v116
	v_exp_f32_e32 v117, v117
	s_waitcnt lgkmcnt(12)
	v_mfma_f32_32x32x16_bf16 v[34:49], v[154:157], v[60:63], v[34:49]
	v_exp_f32_e32 v118, v118
	v_exp_f32_e32 v119, v119
	v_exp_f32_e32 v120, v120
	v_exp_f32_e32 v121, v121
	ds_read_b128 v[60:63], v230 offset:16384
	ds_read_b128 v[162:165], v230 offset:16896
	s_waitcnt lgkmcnt(12)
	v_mfma_f32_32x32x16_bf16 v[18:33], v[146:149], v[82:85], v[18:33]
	v_exp_f32_e32 v122, v122
	v_exp_f32_e32 v123, v123
	v_exp_f32_e32 v124, v124
	v_exp_f32_e32 v125, v125
	ds_read_b128 v[166:169], v230 offset:18432
	ds_read_b128 v[170:173], v230 offset:18944
	s_waitcnt lgkmcnt(12)
	v_mfma_f32_32x32x16_bf16 v[34:49], v[146:149], v[86:89], v[34:49]
	v_exp_f32_e32 v126, v126
	v_exp_f32_e32 v127, v127
	v_exp_f32_e32 v128, v128
	v_exp_f32_e32 v129, v129
	ds_read_b128 v[174:177], v230 offset:20480
	ds_read_b128 v[178:181], v230 offset:20992
	s_waitcnt lgkmcnt(12)
	v_mfma_f32_32x32x16_bf16 v[18:33], v[138:141], v[90:93], v[18:33]
	v_exp_f32_e32 v98, v98
	v_exp_f32_e32 v99, v99
	v_exp_f32_e32 v100, v100
	v_exp_f32_e32 v101, v101
	ds_read_b128 v[182:185], v230 offset:22528
	ds_read_b128 v[52:55], v230 offset:23040
	s_waitcnt lgkmcnt(12)
	v_mfma_f32_32x32x16_bf16 v[34:49], v[138:141], v[64:67], v[34:49]
	v_exp_f32_e32 v102, v102
	v_exp_f32_e32 v103, v103
	v_exp_f32_e32 v104, v104
	v_exp_f32_e32 v105, v105
	s_waitcnt lgkmcnt(10)
	v_mfma_f32_32x32x16_bf16 v[18:33], v[130:133], v[68:71], v[18:33]
	v_exp_f32_e32 v106, v106
	v_exp_f32_e32 v107, v107
	v_exp_f32_e32 v108, v108
	v_exp_f32_e32 v109, v109
	s_waitcnt lgkmcnt(8)
	v_mfma_f32_32x32x16_bf16 v[34:49], v[130:133], v[72:75], v[34:49]
	v_exp_f32_e32 v110, v110
	v_exp_f32_e32 v111, v111
	v_exp_f32_e32 v112, v112
	v_exp_f32_e32 v113, v113
	s_waitcnt vmcnt(2) lgkmcnt(0)
	s_barrier
; #define WAIT_BAR(N) asm volatile("s_waitcnt vmcnt(" #N ") lgkmcnt(0)\n\ts_barrier":::"memory")
;   #define RESC() do{ if(resc){ asm volatile("s_waitcnt lgkmcnt(0)":::"memory"); \
;       _Pragma("unroll") for(int d_=0;d_<2;++d_) _Pragma("unroll") for(int r=0;r<16;++r)o[d_][r]*=wsf[crow(r,hi)]; } }while(0)
;   #define ROT() do{sl_prev=sl_cur;sl_cur=sl_next;sl_next=(sl_next==(NSLOT-1)*SLOTB)?0:sl_next+SLOTB;}while(0)
; template<int THRL,bool FIXREF> __device__ __forceinline__ void attn_unit(const float*gq,const float*tab,const int tq0,const bf16*Qw0,const bf16*__restrict__ Kl,const bf16*__restrict__ Vl,const int NT,bf16*Ow0,char*shm){
;     ...
;   int t=1;
;     ...
;   for(;t+5<NT;t+=2){
;     STEP(pB0,pB1,pA0,pA1,t,true,true,true);     WAIT_BAR(2); RESC(); ROT();
;     STEP(pA0,pA1,pB0,pB1,t+1,true,true,true);   WAIT_BAR(2); RESC(); ROT();
	ds_read_b64_tr_b16 v[186:187], v233 offset:32768
	ds_read_b64_tr_b16 v[188:189], v233 offset:33280
	s_waitcnt lgkmcnt(9)
	v_mfma_f32_32x32x16_bf16 v[82:97], v[60:63], v[158:161], v[2:17]
	v_add_f32_e32 v65, v114, v115
	v_add_f32_e32 v65, v116, v65
	v_add_f32_e32 v65, v117, v65
	v_add_f32_e32 v65, v118, v65
	v_add_f32_e32 v65, v119, v65
	v_cvt_pk_bf16_f32 v154, v114, v115
	v_cvt_pk_bf16_f32 v155, v116, v117
	ds_read_b64_tr_b16 v[60:61], v233 offset:36864
	ds_read_b64_tr_b16 v[62:63], v233 offset:37376
	s_waitcnt lgkmcnt(10)
	v_mfma_f32_32x32x16_bf16 v[66:81], v[162:165], v[158:161], v[2:17]
	v_add_f32_e32 v65, v120, v65
	v_add_f32_e32 v65, v121, v65
	v_add_f32_e32 v65, v122, v65
	v_add_f32_e32 v65, v123, v65
	v_cvt_pk_bf16_f32 v156, v118, v119
	v_cvt_pk_bf16_f32 v157, v120, v121
	ds_read_b64_tr_b16 v[114:115], v233 offset:33792
	ds_read_b64_tr_b16 v[116:117], v233 offset:34304
	s_waitcnt lgkmcnt(11)
	v_mfma_f32_32x32x16_bf16 v[82:97], v[166:169], v[150:153], v[82:97]
	v_add_f32_e32 v65, v124, v65
	v_add_f32_e32 v65, v125, v65
	v_add_f32_e32 v65, v126, v65
	v_add_f32_e32 v65, v127, v65
	v_cvt_pk_bf16_f32 v146, v122, v123
	v_cvt_pk_bf16_f32 v147, v124, v125
	ds_read_b64_tr_b16 v[118:119], v233 offset:37888
	ds_read_b64_tr_b16 v[120:121], v233 offset:38400
	s_waitcnt lgkmcnt(12)
	v_mfma_f32_32x32x16_bf16 v[66:81], v[170:173], v[150:153], v[66:81]
	v_add_f32_e32 v65, v128, v65
	v_add_f32_e32 v65, v129, v65
	v_add_f32_e32 v65, v98, v65
	v_add_f32_e32 v65, v99, v65
	v_cvt_pk_bf16_f32 v148, v126, v127
	v_cvt_pk_bf16_f32 v149, v128, v129
	ds_read_b64_tr_b16 v[122:123], v233 offset:34816
	ds_read_b64_tr_b16 v[124:125], v233 offset:35328
	s_waitcnt lgkmcnt(13)
	v_mfma_f32_32x32x16_bf16 v[82:97], v[174:177], v[142:145], v[82:97]
	v_add_f32_e32 v65, v100, v65
	v_add_f32_e32 v65, v101, v65
	v_add_f32_e32 v65, v102, v65
	v_add_f32_e32 v65, v103, v65
	v_cvt_pk_bf16_f32 v138, v98, v99
	v_cvt_pk_bf16_f32 v139, v100, v101
	ds_read_b64_tr_b16 v[98:99], v233 offset:38912
	ds_read_b64_tr_b16 v[100:101], v233 offset:39424
	s_waitcnt lgkmcnt(14)
	v_mfma_f32_32x32x16_bf16 v[66:81], v[178:181], v[142:145], v[66:81]
	v_add_f32_e32 v65, v104, v65
	v_add_f32_e32 v65, v105, v65
	v_add_f32_e32 v65, v106, v65
	v_add_f32_e32 v65, v107, v65
	v_cvt_pk_bf16_f32 v140, v102, v103
	v_cvt_pk_bf16_f32 v141, v104, v105
	ds_read_b64_tr_b16 v[102:103], v233 offset:35840
	ds_read_b64_tr_b16 v[104:105], v233 offset:36352
	s_waitcnt lgkmcnt(14)
	v_mfma_f32_32x32x16_bf16 v[82:97], v[182:185], v[134:137], v[82:97]
	v_add_f32_e32 v65, v108, v65
	v_add_f32_e32 v65, v109, v65
	v_add_f32_e32 v65, v110, v65
	v_add_f32_e32 v65, v111, v65
	v_cvt_pk_bf16_f32 v130, v106, v107
	v_cvt_pk_bf16_f32 v131, v108, v109
	ds_read_b64_tr_b16 v[106:107], v233 offset:39936
	ds_read_b64_tr_b16 v[108:109], v233 offset:40448
	v_mfma_f32_32x32x16_bf16 v[66:81], v[52:55], v[134:137], v[66:81]
	v_add_f32_e32 v52, v112, v65
	v_add_f32_e32 v52, v113, v52
	v_cvt_pk_bf16_f32 v132, v110, v111
	v_cvt_pk_bf16_f32 v133, v112, v113
	s_add_i32 m0, s18, 0x4000
	s_nop 0
	global_load_lds_dwordx4 v240, s[100:101]
	s_mov_b32 m0, s19
	s_nop 0
	global_load_lds_dwordx4 v241, s[100:101]
	s_waitcnt lgkmcnt(14)
	v_mfma_f32_32x32x16_bf16 v[18:33], v[154:157], v[186:189], v[18:33]
	s_add_u32 s100, s100, 0x2000
	s_addc_u32 s101, s101, 0
	v_exp_f32_e32 v82, v82
	v_exp_f32_e32 v83, v83
	v_exp_f32_e32 v84, v84
	v_exp_f32_e32 v85, v85
	s_waitcnt lgkmcnt(12)
	v_mfma_f32_32x32x16_bf16 v[34:49], v[154:157], v[60:63], v[34:49]
	v_exp_f32_e32 v86, v86
	v_exp_f32_e32 v87, v87
	v_exp_f32_e32 v88, v88
	v_exp_f32_e32 v89, v89
	ds_read_b128 v[190:193], v230
	ds_read_b128 v[186:189], v230 offset:512
	s_waitcnt lgkmcnt(12)
	v_mfma_f32_32x32x16_bf16 v[18:33], v[146:149], v[114:117], v[18:33]
	v_exp_f32_e32 v90, v90
	v_exp_f32_e32 v91, v91
	v_exp_f32_e32 v92, v92
	v_exp_f32_e32 v93, v93
	ds_read_b128 v[182:185], v230 offset:2048
	ds_read_b128 v[178:181], v230 offset:2560
	s_waitcnt lgkmcnt(12)
	v_mfma_f32_32x32x16_bf16 v[34:49], v[146:149], v[118:121], v[34:49]
	v_exp_f32_e32 v94, v94
	v_exp_f32_e32 v95, v95
	v_exp_f32_e32 v96, v96
	v_exp_f32_e32 v97, v97
	ds_read_b128 v[174:177], v230 offset:4096
	ds_read_b128 v[170:173], v230 offset:4608
	s_waitcnt lgkmcnt(12)
	v_mfma_f32_32x32x16_bf16 v[18:33], v[138:141], v[122:125], v[18:33]
	v_exp_f32_e32 v66, v66
	v_exp_f32_e32 v67, v67
	v_exp_f32_e32 v68, v68
	v_exp_f32_e32 v69, v69
	ds_read_b128 v[166:169], v230 offset:6144
	ds_read_b128 v[162:165], v230 offset:6656
	s_waitcnt lgkmcnt(12)
	v_mfma_f32_32x32x16_bf16 v[34:49], v[138:141], v[98:101], v[34:49]
	v_exp_f32_e32 v70, v70
	v_exp_f32_e32 v71, v71
	v_exp_f32_e32 v72, v72
	v_exp_f32_e32 v73, v73
	s_waitcnt lgkmcnt(10)
	v_mfma_f32_32x32x16_bf16 v[18:33], v[130:133], v[102:105], v[18:33]
	v_exp_f32_e32 v74, v74
	v_exp_f32_e32 v75, v75
	v_exp_f32_e32 v76, v76
	v_exp_f32_e32 v77, v77
	s_waitcnt lgkmcnt(8)
	v_mfma_f32_32x32x16_bf16 v[34:49], v[130:133], v[106:109], v[34:49]
	v_exp_f32_e32 v78, v78
	v_exp_f32_e32 v79, v79
	v_exp_f32_e32 v80, v80
	v_exp_f32_e32 v81, v81
	s_waitcnt vmcnt(2) lgkmcnt(0)
	s_barrier
; #define WAIT_BAR(N) asm volatile("s_waitcnt vmcnt(" #N ") lgkmcnt(0)\n\ts_barrier":::"memory")
;   #define RESC() do{ if(resc){ asm volatile("s_waitcnt lgkmcnt(0)":::"memory"); \
;       _Pragma("unroll") for(int d_=0;d_<2;++d_) _Pragma("unroll") for(int r=0;r<16;++r)o[d_][r]*=wsf[crow(r,hi)]; } }while(0)
;   #define ROT() do{sl_prev=sl_cur;sl_cur=sl_next;sl_next=(sl_next==(NSLOT-1)*SLOTB)?0:sl_next+SLOTB;}while(0)
; template<int THRL,bool FIXREF> __device__ __forceinline__ void attn_unit(const float*gq,const float*tab,const int tq0,const bf16*Qw0,const bf16*__restrict__ Kl,const bf16*__restrict__ Vl,const int NT,bf16*Ow0,char*shm){
;     ...
;   int t=1;
;     ...
;   for(;t+5<NT;t+=2){
;     STEP(pB0,pB1,pA0,pA1,t,true,true,true);     WAIT_BAR(2); RESC(); ROT();
;     STEP(pA0,pA1,pB0,pB1,t+1,true,true,true);   WAIT_BAR(2); RESC(); ROT();
	v_add_f32_e32 v50, v50, v51
	v_add_f32_e32 v50, v50, v52
	ds_read_b64_tr_b16 v[52:53], v233 offset:40960
	ds_read_b64_tr_b16 v[54:55], v233 offset:41472
	v_add_f32_e32 v60, v82, v83
	v_add_f32_e32 v60, v84, v60
	v_add_f32_e32 v60, v85, v60
	v_add_f32_e32 v60, v86, v60
	v_add_f32_e32 v64, v87, v60
	v_cvt_pk_bf16_f32 v154, v82, v83
	v_cvt_pk_bf16_f32 v155, v84, v85
	s_waitcnt lgkmcnt(9)
	v_mfma_f32_32x32x16_bf16 v[114:129], v[190:193], v[158:161], v[2:17]
	ds_read_b64_tr_b16 v[60:61], v233 offset:45056
	ds_read_b64_tr_b16 v[62:63], v233 offset:45568
	v_add_f32_e32 v64, v88, v64
	v_add_f32_e32 v64, v89, v64
	v_add_f32_e32 v64, v90, v64
	v_add_f32_e32 v64, v91, v64
	v_cvt_pk_bf16_f32 v156, v86, v87
	v_cvt_pk_bf16_f32 v157, v88, v89
	s_waitcnt lgkmcnt(10)
	v_mfma_f32_32x32x16_bf16 v[98:113], v[186:189], v[158:161], v[2:17]
	ds_read_b64_tr_b16 v[82:83], v233 offset:41984
	ds_read_b64_tr_b16 v[84:85], v233 offset:42496
	v_add_f32_e32 v64, v92, v64
	v_add_f32_e32 v64, v93, v64
	v_add_f32_e32 v64, v94, v64
	v_add_f32_e32 v64, v95, v64
	v_cvt_pk_bf16_f32 v146, v90, v91
	v_cvt_pk_bf16_f32 v147, v92, v93
	s_waitcnt lgkmcnt(11)
	v_mfma_f32_32x32x16_bf16 v[114:129], v[182:185], v[150:153], v[114:129]
	ds_read_b64_tr_b16 v[86:87], v233 offset:46080
	ds_read_b64_tr_b16 v[88:89], v233 offset:46592
	v_add_f32_e32 v64, v96, v64
	v_add_f32_e32 v64, v97, v64
	v_add_f32_e32 v64, v66, v64
	v_add_f32_e32 v64, v67, v64
	v_cvt_pk_bf16_f32 v148, v94, v95
	v_cvt_pk_bf16_f32 v149, v96, v97
	s_waitcnt lgkmcnt(12)
	v_mfma_f32_32x32x16_bf16 v[98:113], v[178:181], v[150:153], v[98:113]
	ds_read_b64_tr_b16 v[90:91], v233 offset:43008
	ds_read_b64_tr_b16 v[92:93], v233 offset:43520
	v_add_f32_e32 v64, v68, v64
	v_add_f32_e32 v64, v69, v64
	v_add_f32_e32 v64, v70, v64
	v_add_f32_e32 v94, v71, v64
	v_cvt_pk_bf16_f32 v138, v66, v67
	v_cvt_pk_bf16_f32 v139, v68, v69
	s_waitcnt lgkmcnt(13)
	v_mfma_f32_32x32x16_bf16 v[114:129], v[174:177], v[142:145], v[114:129]
	ds_read_b64_tr_b16 v[64:65], v233 offset:47104
	ds_read_b64_tr_b16 v[66:67], v233 offset:47616
	v_add_f32_e32 v68, v72, v94
	v_add_f32_e32 v68, v73, v68
	v_add_f32_e32 v68, v74, v68
	v_add_f32_e32 v94, v75, v68
	v_cvt_pk_bf16_f32 v140, v70, v71
	v_cvt_pk_bf16_f32 v141, v72, v73
	s_waitcnt lgkmcnt(14)
	v_mfma_f32_32x32x16_bf16 v[98:113], v[170:173], v[142:145], v[98:113]
	ds_read_b64_tr_b16 v[68:69], v233 offset:44032
	ds_read_b64_tr_b16 v[70:71], v233 offset:44544
	v_add_f32_e32 v72, v76, v94
	v_add_f32_e32 v72, v77, v72
	v_add_f32_e32 v72, v78, v72
	v_add_f32_e32 v94, v79, v72
	v_cvt_pk_bf16_f32 v130, v74, v75
	v_cvt_pk_bf16_f32 v131, v76, v77
	s_waitcnt lgkmcnt(14)
	v_mfma_f32_32x32x16_bf16 v[114:129], v[166:169], v[134:137], v[114:129]
	ds_read_b64_tr_b16 v[72:73], v233 offset:48128
	ds_read_b64_tr_b16 v[74:75], v233 offset:48640
	v_add_f32_e32 v51, v80, v94
	v_add_f32_e32 v51, v81, v51
	v_cvt_pk_bf16_f32 v132, v78, v79
	v_cvt_pk_bf16_f32 v133, v80, v81
	v_mfma_f32_32x32x16_bf16 v[98:113], v[162:165], v[134:137], v[98:113]
	s_mov_b32 m0, s18
	s_nop 0
	global_load_lds_dwordx4 v240, s[100:101]
	s_add_i32 m0, s19, 0x2000
	s_nop 0
	global_load_lds_dwordx4 v241, s[100:101]
	s_waitcnt lgkmcnt(14)
	v_mfma_f32_32x32x16_bf16 v[18:33], v[154:157], v[52:55], v[18:33]
	s_add_u32 s100, s100, 0x2000
	s_addc_u32 s101, s101, 0
	v_exp_f32_e32 v114, v114
	v_exp_f32_e32 v115, v115
	v_exp_f32_e32 v116, v116
	v_exp_f32_e32 v117, v117
	s_waitcnt lgkmcnt(12)
	v_mfma_f32_32x32x16_bf16 v[34:49], v[154:157], v[60:63], v[34:49]
	v_exp_f32_e32 v118, v118
	v_exp_f32_e32 v119, v119
	v_exp_f32_e32 v120, v120
	v_exp_f32_e32 v121, v121
	ds_read_b128 v[60:63], v230 offset:8192
	ds_read_b128 v[162:165], v230 offset:8704
	s_waitcnt lgkmcnt(12)
	v_mfma_f32_32x32x16_bf16 v[18:33], v[146:149], v[82:85], v[18:33]
	v_exp_f32_e32 v122, v122
	v_exp_f32_e32 v123, v123
	v_exp_f32_e32 v124, v124
	v_exp_f32_e32 v125, v125
	ds_read_b128 v[166:169], v230 offset:10240
	ds_read_b128 v[170:173], v230 offset:10752
	s_waitcnt lgkmcnt(12)
	v_mfma_f32_32x32x16_bf16 v[34:49], v[146:149], v[86:89], v[34:49]
	v_exp_f32_e32 v126, v126
	v_exp_f32_e32 v127, v127
	v_exp_f32_e32 v128, v128
	v_exp_f32_e32 v129, v129
	ds_read_b128 v[174:177], v230 offset:12288
	ds_read_b128 v[178:181], v230 offset:12800
	s_waitcnt lgkmcnt(12)
	v_mfma_f32_32x32x16_bf16 v[18:33], v[138:141], v[90:93], v[18:33]
	v_exp_f32_e32 v98, v98
	v_exp_f32_e32 v99, v99
	v_exp_f32_e32 v100, v100
	v_exp_f32_e32 v101, v101
	ds_read_b128 v[182:185], v230 offset:14336
	ds_read_b128 v[52:55], v230 offset:14848
	s_waitcnt lgkmcnt(12)
	v_mfma_f32_32x32x16_bf16 v[34:49], v[138:141], v[64:67], v[34:49]
	v_exp_f32_e32 v102, v102
	v_exp_f32_e32 v103, v103
	v_exp_f32_e32 v104, v104
	v_exp_f32_e32 v105, v105
	s_waitcnt lgkmcnt(10)
	v_mfma_f32_32x32x16_bf16 v[18:33], v[130:133], v[68:71], v[18:33]
	v_exp_f32_e32 v106, v106
	v_exp_f32_e32 v107, v107
	v_exp_f32_e32 v108, v108
	v_exp_f32_e32 v109, v109
	s_waitcnt lgkmcnt(8)
	v_mfma_f32_32x32x16_bf16 v[34:49], v[130:133], v[72:75], v[34:49]
	v_exp_f32_e32 v110, v110
	v_exp_f32_e32 v111, v111
	v_exp_f32_e32 v112, v112
	v_exp_f32_e32 v113, v113
	s_waitcnt vmcnt(2) lgkmcnt(0)
	s_barrier
; #define WAIT_BAR(N) asm volatile("s_waitcnt vmcnt(" #N ") lgkmcnt(0)\n\ts_barrier":::"memory")
;   #define RESC() do{ if(resc){ asm volatile("s_waitcnt lgkmcnt(0)":::"memory"); \
;       _Pragma("unroll") for(int d_=0;d_<2;++d_) _Pragma("unroll") for(int r=0;r<16;++r)o[d_][r]*=wsf[crow(r,hi)]; } }while(0)
;   #define ROT() do{sl_prev=sl_cur;sl_cur=sl_next;sl_next=(sl_next==(NSLOT-1)*SLOTB)?0:sl_next+SLOTB;}while(0)
; template<int THRL,bool FIXREF> __device__ __forceinline__ void attn_unit(const float*gq,const float*tab,const int tq0,const bf16*Qw0,const bf16*__restrict__ Kl,const bf16*__restrict__ Vl,const int NT,bf16*Ow0,char*shm){
;     ...
;   int t=1;
;     ...
;   for(;t+5<NT;t+=2){
;     STEP(pB0,pB1,pA0,pA1,t,true,true,true);     WAIT_BAR(2); RESC(); ROT();
;     STEP(pA0,pA1,pB0,pB1,t+1,true,true,true);   WAIT_BAR(2); RESC(); ROT();
	ds_read_b64_tr_b16 v[186:187], v233 offset:24576
	ds_read_b64_tr_b16 v[188:189], v233 offset:25088
	s_waitcnt lgkmcnt(9)
	v_mfma_f32_32x32x16_bf16 v[82:97], v[60:63], v[158:161], v[2:17]
	v_add_f32_e32 v65, v114, v115
	v_add_f32_e32 v65, v116, v65
	v_add_f32_e32 v65, v117, v65
	v_add_f32_e32 v65, v118, v65
	v_add_f32_e32 v65, v119, v65
	v_cvt_pk_bf16_f32 v154, v114, v115
	v_cvt_pk_bf16_f32 v155, v116, v117
	ds_read_b64_tr_b16 v[60:61], v233 offset:28672
	ds_read_b64_tr_b16 v[62:63], v233 offset:29184
	s_waitcnt lgkmcnt(10)
	v_mfma_f32_32x32x16_bf16 v[66:81], v[162:165], v[158:161], v[2:17]
	v_add_f32_e32 v65, v120, v65
	v_add_f32_e32 v65, v121, v65
	v_add_f32_e32 v65, v122, v65
	v_add_f32_e32 v65, v123, v65
	v_cvt_pk_bf16_f32 v156, v118, v119
	v_cvt_pk_bf16_f32 v157, v120, v121
	ds_read_b64_tr_b16 v[114:115], v233 offset:25600
	ds_read_b64_tr_b16 v[116:117], v233 offset:26112
	s_waitcnt lgkmcnt(11)
	v_mfma_f32_32x32x16_bf16 v[82:97], v[166:169], v[150:153], v[82:97]
	v_add_f32_e32 v65, v124, v65
	v_add_f32_e32 v65, v125, v65
	v_add_f32_e32 v65, v126, v65
	v_add_f32_e32 v65, v127, v65
	v_cvt_pk_bf16_f32 v146, v122, v123
	v_cvt_pk_bf16_f32 v147, v124, v125
	ds_read_b64_tr_b16 v[118:119], v233 offset:29696
	ds_read_b64_tr_b16 v[120:121], v233 offset:30208
	s_waitcnt lgkmcnt(12)
	v_mfma_f32_32x32x16_bf16 v[66:81], v[170:173], v[150:153], v[66:81]
	v_add_f32_e32 v65, v128, v65
	v_add_f32_e32 v65, v129, v65
	v_add_f32_e32 v65, v98, v65
	v_add_f32_e32 v65, v99, v65
	v_cvt_pk_bf16_f32 v148, v126, v127
	v_cvt_pk_bf16_f32 v149, v128, v129
	ds_read_b64_tr_b16 v[122:123], v233 offset:26624
	ds_read_b64_tr_b16 v[124:125], v233 offset:27136
	s_waitcnt lgkmcnt(13)
	v_mfma_f32_32x32x16_bf16 v[82:97], v[174:177], v[142:145], v[82:97]
	v_add_f32_e32 v65, v100, v65
	v_add_f32_e32 v65, v101, v65
	v_add_f32_e32 v65, v102, v65
	v_add_f32_e32 v65, v103, v65
	v_cvt_pk_bf16_f32 v138, v98, v99
	v_cvt_pk_bf16_f32 v139, v100, v101
	ds_read_b64_tr_b16 v[98:99], v233 offset:30720
	ds_read_b64_tr_b16 v[100:101], v233 offset:31232
	s_waitcnt lgkmcnt(14)
	v_mfma_f32_32x32x16_bf16 v[66:81], v[178:181], v[142:145], v[66:81]
	v_add_f32_e32 v65, v104, v65
	v_add_f32_e32 v65, v105, v65
	v_add_f32_e32 v65, v106, v65
	v_add_f32_e32 v65, v107, v65
	v_cvt_pk_bf16_f32 v140, v102, v103
	v_cvt_pk_bf16_f32 v141, v104, v105
	ds_read_b64_tr_b16 v[102:103], v233 offset:27648
	ds_read_b64_tr_b16 v[104:105], v233 offset:28160
	s_waitcnt lgkmcnt(14)
	v_mfma_f32_32x32x16_bf16 v[82:97], v[182:185], v[134:137], v[82:97]
	v_add_f32_e32 v65, v108, v65
	v_add_f32_e32 v65, v109, v65
	v_add_f32_e32 v65, v110, v65
	v_add_f32_e32 v65, v111, v65
	v_cvt_pk_bf16_f32 v130, v106, v107
	v_cvt_pk_bf16_f32 v131, v108, v109
	ds_read_b64_tr_b16 v[106:107], v233 offset:31744
	ds_read_b64_tr_b16 v[108:109], v233 offset:32256
	v_mfma_f32_32x32x16_bf16 v[66:81], v[52:55], v[134:137], v[66:81]
	v_add_f32_e32 v52, v112, v65
	v_add_f32_e32 v52, v113, v52
	v_cvt_pk_bf16_f32 v132, v110, v111
	v_cvt_pk_bf16_f32 v133, v112, v113
	s_add_i32 m0, s18, 0x2000
	s_nop 0
	global_load_lds_dwordx4 v240, s[100:101]
	s_add_i32 m0, s19, 0x4000
	s_nop 0
	global_load_lds_dwordx4 v241, s[100:101]
	s_waitcnt lgkmcnt(14)
	v_mfma_f32_32x32x16_bf16 v[18:33], v[154:157], v[186:189], v[18:33]
	s_add_u32 s100, s100, 0x2000
	s_addc_u32 s101, s101, 0
	v_exp_f32_e32 v82, v82
	v_exp_f32_e32 v83, v83
	v_exp_f32_e32 v84, v84
	v_exp_f32_e32 v85, v85
	s_waitcnt lgkmcnt(12)
	v_mfma_f32_32x32x16_bf16 v[34:49], v[154:157], v[60:63], v[34:49]
	v_exp_f32_e32 v86, v86
	v_exp_f32_e32 v87, v87
	v_exp_f32_e32 v88, v88
	v_exp_f32_e32 v89, v89
	ds_read_b128 v[190:193], v230 offset:16384
	ds_read_b128 v[186:189], v230 offset:16896
	s_waitcnt lgkmcnt(12)
	v_mfma_f32_32x32x16_bf16 v[18:33], v[146:149], v[114:117], v[18:33]
	v_exp_f32_e32 v90, v90
	v_exp_f32_e32 v91, v91
	v_exp_f32_e32 v92, v92
	v_exp_f32_e32 v93, v93
	ds_read_b128 v[182:185], v230 offset:18432
	ds_read_b128 v[178:181], v230 offset:18944
	s_waitcnt lgkmcnt(12)
	v_mfma_f32_32x32x16_bf16 v[34:49], v[146:149], v[118:121], v[34:49]
	v_exp_f32_e32 v94, v94
	v_exp_f32_e32 v95, v95
	v_exp_f32_e32 v96, v96
	v_exp_f32_e32 v97, v97
	ds_read_b128 v[174:177], v230 offset:20480
	ds_read_b128 v[170:173], v230 offset:20992
	s_waitcnt lgkmcnt(12)
	v_mfma_f32_32x32x16_bf16 v[18:33], v[138:141], v[122:125], v[18:33]
	v_exp_f32_e32 v66, v66
	v_exp_f32_e32 v67, v67
	v_exp_f32_e32 v68, v68
	v_exp_f32_e32 v69, v69
	ds_read_b128 v[166:169], v230 offset:22528
	ds_read_b128 v[162:165], v230 offset:23040
	s_waitcnt lgkmcnt(12)
	v_mfma_f32_32x32x16_bf16 v[34:49], v[138:141], v[98:101], v[34:49]
	v_exp_f32_e32 v70, v70
	v_exp_f32_e32 v71, v71
	v_exp_f32_e32 v72, v72
	v_exp_f32_e32 v73, v73
	s_waitcnt lgkmcnt(10)
	v_mfma_f32_32x32x16_bf16 v[18:33], v[130:133], v[102:105], v[18:33]
	v_exp_f32_e32 v74, v74
	v_exp_f32_e32 v75, v75
	v_exp_f32_e32 v76, v76
	v_exp_f32_e32 v77, v77
	s_waitcnt lgkmcnt(8)
	v_mfma_f32_32x32x16_bf16 v[34:49], v[130:133], v[106:109], v[34:49]
	v_exp_f32_e32 v78, v78
	v_exp_f32_e32 v79, v79
	v_exp_f32_e32 v80, v80
	v_exp_f32_e32 v81, v81
	s_waitcnt vmcnt(2) lgkmcnt(0)
	s_barrier
; #define WAIT_BAR(N) asm volatile("s_waitcnt vmcnt(" #N ") lgkmcnt(0)\n\ts_barrier":::"memory")
;   #define RESC() do{ if(resc){ asm volatile("s_waitcnt lgkmcnt(0)":::"memory"); \
;       _Pragma("unroll") for(int d_=0;d_<2;++d_) _Pragma("unroll") for(int r=0;r<16;++r)o[d_][r]*=wsf[crow(r,hi)]; } }while(0)
;   #define ROT() do{sl_prev=sl_cur;sl_cur=sl_next;sl_next=(sl_next==(NSLOT-1)*SLOTB)?0:sl_next+SLOTB;}while(0)
; template<int THRL,bool FIXREF> __device__ __forceinline__ void attn_unit(const float*gq,const float*tab,const int tq0,const bf16*Qw0,const bf16*__restrict__ Kl,const bf16*__restrict__ Vl,const int NT,bf16*Ow0,char*shm){
;     ...
;   int t=1;
;     ...
;   for(;t+5<NT;t+=2){
;     STEP(pB0,pB1,pA0,pA1,t,true,true,true);     WAIT_BAR(2); RESC(); ROT();
;     STEP(pA0,pA1,pB0,pB1,t+1,true,true,true);   WAIT_BAR(2); RESC(); ROT();
	v_add_f32_e32 v50, v50, v51
	v_add_f32_e32 v50, v50, v52
	ds_read_b64_tr_b16 v[52:53], v233 offset:32768
	ds_read_b64_tr_b16 v[54:55], v233 offset:33280
	v_add_f32_e32 v60, v82, v83
	v_add_f32_e32 v60, v84, v60
	v_add_f32_e32 v60, v85, v60
	v_add_f32_e32 v60, v86, v60
	v_add_f32_e32 v64, v87, v60
	v_cvt_pk_bf16_f32 v154, v82, v83
	v_cvt_pk_bf16_f32 v155, v84, v85
	s_waitcnt lgkmcnt(9)
	v_mfma_f32_32x32x16_bf16 v[114:129], v[190:193], v[158:161], v[2:17]
	ds_read_b64_tr_b16 v[60:61], v233 offset:36864
	ds_read_b64_tr_b16 v[62:63], v233 offset:37376
	v_add_f32_e32 v64, v88, v64
	v_add_f32_e32 v64, v89, v64
	v_add_f32_e32 v64, v90, v64
	v_add_f32_e32 v64, v91, v64
	v_cvt_pk_bf16_f32 v156, v86, v87
	v_cvt_pk_bf16_f32 v157, v88, v89
	s_waitcnt lgkmcnt(10)
	v_mfma_f32_32x32x16_bf16 v[98:113], v[186:189], v[158:161], v[2:17]
	ds_read_b64_tr_b16 v[82:83], v233 offset:33792
	ds_read_b64_tr_b16 v[84:85], v233 offset:34304
	v_add_f32_e32 v64, v92, v64
	v_add_f32_e32 v64, v93, v64
	v_add_f32_e32 v64, v94, v64
	v_add_f32_e32 v64, v95, v64
	v_cvt_pk_bf16_f32 v146, v90, v91
	v_cvt_pk_bf16_f32 v147, v92, v93
	s_waitcnt lgkmcnt(11)
	v_mfma_f32_32x32x16_bf16 v[114:129], v[182:185], v[150:153], v[114:129]
	ds_read_b64_tr_b16 v[86:87], v233 offset:37888
	ds_read_b64_tr_b16 v[88:89], v233 offset:38400
	v_add_f32_e32 v64, v96, v64
	v_add_f32_e32 v64, v97, v64
	v_add_f32_e32 v64, v66, v64
	v_add_f32_e32 v64, v67, v64
	v_cvt_pk_bf16_f32 v148, v94, v95
	v_cvt_pk_bf16_f32 v149, v96, v97
	s_waitcnt lgkmcnt(12)
	v_mfma_f32_32x32x16_bf16 v[98:113], v[178:181], v[150:153], v[98:113]
	ds_read_b64_tr_b16 v[90:91], v233 offset:34816
	ds_read_b64_tr_b16 v[92:93], v233 offset:35328
	v_add_f32_e32 v64, v68, v64
	v_add_f32_e32 v64, v69, v64
	v_add_f32_e32 v64, v70, v64
	v_add_f32_e32 v94, v71, v64
	v_cvt_pk_bf16_f32 v138, v66, v67
	v_cvt_pk_bf16_f32 v139, v68, v69
	s_waitcnt lgkmcnt(13)
	v_mfma_f32_32x32x16_bf16 v[114:129], v[174:177], v[142:145], v[114:129]
	ds_read_b64_tr_b16 v[64:65], v233 offset:38912
	ds_read_b64_tr_b16 v[66:67], v233 offset:39424
	v_add_f32_e32 v68, v72, v94
	v_add_f32_e32 v68, v73, v68
	v_add_f32_e32 v68, v74, v68
	v_add_f32_e32 v94, v75, v68
	v_cvt_pk_bf16_f32 v140, v70, v71
	v_cvt_pk_bf16_f32 v141, v72, v73
	s_waitcnt lgkmcnt(14)
	v_mfma_f32_32x32x16_bf16 v[98:113], v[170:173], v[142:145], v[98:113]
	ds_read_b64_tr_b16 v[68:69], v233 offset:35840
	ds_read_b64_tr_b16 v[70:71], v233 offset:36352
	v_add_f32_e32 v72, v76, v94
	v_add_f32_e32 v72, v77, v72
	v_add_f32_e32 v72, v78, v72
	v_add_f32_e32 v94, v79, v72
	v_cvt_pk_bf16_f32 v130, v74, v75
	v_cvt_pk_bf16_f32 v131, v76, v77
	s_waitcnt lgkmcnt(14)
	v_mfma_f32_32x32x16_bf16 v[114:129], v[166:169], v[134:137], v[114:129]
	ds_read_b64_tr_b16 v[72:73], v233 offset:39936
	ds_read_b64_tr_b16 v[74:75], v233 offset:40448
	v_add_f32_e32 v51, v80, v94
	v_add_f32_e32 v51, v81, v51
	v_cvt_pk_bf16_f32 v132, v78, v79
	v_cvt_pk_bf16_f32 v133, v80, v81
	v_mfma_f32_32x32x16_bf16 v[98:113], v[162:165], v[134:137], v[98:113]
	s_add_i32 m0, s18, 0x4000
	s_nop 0
	global_load_lds_dwordx4 v240, s[100:101]
	s_mov_b32 m0, s19
	s_nop 0
	global_load_lds_dwordx4 v241, s[100:101]
	s_waitcnt lgkmcnt(14)
	v_mfma_f32_32x32x16_bf16 v[18:33], v[154:157], v[52:55], v[18:33]
	s_add_u32 s100, s100, 0x2000
	s_addc_u32 s101, s101, 0
	v_exp_f32_e32 v114, v114
	v_exp_f32_e32 v115, v115
	v_exp_f32_e32 v116, v116
	v_exp_f32_e32 v117, v117
	s_waitcnt lgkmcnt(12)
	v_mfma_f32_32x32x16_bf16 v[34:49], v[154:157], v[60:63], v[34:49]
	v_exp_f32_e32 v118, v118
	v_exp_f32_e32 v119, v119
	v_exp_f32_e32 v120, v120
	v_exp_f32_e32 v121, v121
	ds_read_b128 v[60:63], v230
	ds_read_b128 v[162:165], v230 offset:512
	s_waitcnt lgkmcnt(12)
	v_mfma_f32_32x32x16_bf16 v[18:33], v[146:149], v[82:85], v[18:33]
	v_exp_f32_e32 v122, v122
	v_exp_f32_e32 v123, v123
	v_exp_f32_e32 v124, v124
	v_exp_f32_e32 v125, v125
	ds_read_b128 v[166:169], v230 offset:2048
	ds_read_b128 v[170:173], v230 offset:2560
	s_waitcnt lgkmcnt(12)
	v_mfma_f32_32x32x16_bf16 v[34:49], v[146:149], v[86:89], v[34:49]
	v_exp_f32_e32 v126, v126
	v_exp_f32_e32 v127, v127
	v_exp_f32_e32 v128, v128
	v_exp_f32_e32 v129, v129
	ds_read_b128 v[174:177], v230 offset:4096
	ds_read_b128 v[178:181], v230 offset:4608
	s_waitcnt lgkmcnt(12)
	v_mfma_f32_32x32x16_bf16 v[18:33], v[138:141], v[90:93], v[18:33]
	v_exp_f32_e32 v98, v98
	v_exp_f32_e32 v99, v99
	v_exp_f32_e32 v100, v100
	v_exp_f32_e32 v101, v101
	ds_read_b128 v[182:185], v230 offset:6144
	ds_read_b128 v[52:55], v230 offset:6656
	s_waitcnt lgkmcnt(12)
	v_mfma_f32_32x32x16_bf16 v[34:49], v[138:141], v[64:67], v[34:49]
	v_exp_f32_e32 v102, v102
	v_exp_f32_e32 v103, v103
	v_exp_f32_e32 v104, v104
	v_exp_f32_e32 v105, v105
	s_waitcnt lgkmcnt(10)
	v_mfma_f32_32x32x16_bf16 v[18:33], v[130:133], v[68:71], v[18:33]
	v_exp_f32_e32 v106, v106
	v_exp_f32_e32 v107, v107
	v_exp_f32_e32 v108, v108
	v_exp_f32_e32 v109, v109
	s_waitcnt lgkmcnt(8)
	v_mfma_f32_32x32x16_bf16 v[34:49], v[130:133], v[72:75], v[34:49]
	v_exp_f32_e32 v110, v110
	v_exp_f32_e32 v111, v111
	v_exp_f32_e32 v112, v112
	v_exp_f32_e32 v113, v113
	s_waitcnt vmcnt(2) lgkmcnt(0)
	s_barrier
; #define WAIT_BAR(N) asm volatile("s_waitcnt vmcnt(" #N ") lgkmcnt(0)\n\ts_barrier":::"memory")
;   #define RESC() do{ if(resc){ asm volatile("s_waitcnt lgkmcnt(0)":::"memory"); \
;       _Pragma("unroll") for(int d_=0;d_<2;++d_) _Pragma("unroll") for(int r=0;r<16;++r)o[d_][r]*=wsf[crow(r,hi)]; } }while(0)
;   #define ROT() do{sl_prev=sl_cur;sl_cur=sl_next;sl_next=(sl_next==(NSLOT-1)*SLOTB)?0:sl_next+SLOTB;}while(0)
; template<int THRL,bool FIXREF> __device__ __forceinline__ void attn_unit(const float*gq,const float*tab,const int tq0,const bf16*Qw0,const bf16*__restrict__ Kl,const bf16*__restrict__ Vl,const int NT,bf16*Ow0,char*shm){
;     ...
;   int t=1;
;     ...
;   for(;t+5<NT;t+=2){
;     STEP(pB0,pB1,pA0,pA1,t,true,true,true);     WAIT_BAR(2); RESC(); ROT();
;     STEP(pA0,pA1,pB0,pB1,t+1,true,true,true);   WAIT_BAR(2); RESC(); ROT();
	ds_read_b64_tr_b16 v[186:187], v233 offset:40960
	ds_read_b64_tr_b16 v[188:189], v233 offset:41472
	s_waitcnt lgkmcnt(9)
	v_mfma_f32_32x32x16_bf16 v[82:97], v[60:63], v[158:161], v[2:17]
	v_add_f32_e32 v65, v114, v115
	v_add_f32_e32 v65, v116, v65
	v_add_f32_e32 v65, v117, v65
	v_add_f32_e32 v65, v118, v65
	v_add_f32_e32 v65, v119, v65
	v_cvt_pk_bf16_f32 v154, v114, v115
	v_cvt_pk_bf16_f32 v155, v116, v117
	ds_read_b64_tr_b16 v[60:61], v233 offset:45056
	ds_read_b64_tr_b16 v[62:63], v233 offset:45568
	s_waitcnt lgkmcnt(10)
	v_mfma_f32_32x32x16_bf16 v[66:81], v[162:165], v[158:161], v[2:17]
	v_add_f32_e32 v65, v120, v65
	v_add_f32_e32 v65, v121, v65
	v_add_f32_e32 v65, v122, v65
	v_add_f32_e32 v65, v123, v65
	v_cvt_pk_bf16_f32 v156, v118, v119
	v_cvt_pk_bf16_f32 v157, v120, v121
	ds_read_b64_tr_b16 v[114:115], v233 offset:41984
	ds_read_b64_tr_b16 v[116:117], v233 offset:42496
	s_waitcnt lgkmcnt(11)
	v_mfma_f32_32x32x16_bf16 v[82:97], v[166:169], v[150:153], v[82:97]
	v_add_f32_e32 v65, v124, v65
	v_add_f32_e32 v65, v125, v65
	v_add_f32_e32 v65, v126, v65
	v_add_f32_e32 v65, v127, v65
	v_cvt_pk_bf16_f32 v146, v122, v123
	v_cvt_pk_bf16_f32 v147, v124, v125
	ds_read_b64_tr_b16 v[118:119], v233 offset:46080
	ds_read_b64_tr_b16 v[120:121], v233 offset:46592
	s_waitcnt lgkmcnt(12)
	v_mfma_f32_32x32x16_bf16 v[66:81], v[170:173], v[150:153], v[66:81]
	v_add_f32_e32 v65, v128, v65
	v_add_f32_e32 v65, v129, v65
	v_add_f32_e32 v65, v98, v65
	v_add_f32_e32 v65, v99, v65
	v_cvt_pk_bf16_f32 v148, v126, v127
	v_cvt_pk_bf16_f32 v149, v128, v129
	ds_read_b64_tr_b16 v[122:123], v233 offset:43008
	ds_read_b64_tr_b16 v[124:125], v233 offset:43520
	s_waitcnt lgkmcnt(13)
	v_mfma_f32_32x32x16_bf16 v[82:97], v[174:177], v[142:145], v[82:97]
	v_add_f32_e32 v65, v100, v65
	v_add_f32_e32 v65, v101, v65
	v_add_f32_e32 v65, v102, v65
	v_add_f32_e32 v65, v103, v65
	v_cvt_pk_bf16_f32 v138, v98, v99
	v_cvt_pk_bf16_f32 v139, v100, v101
	ds_read_b64_tr_b16 v[98:99], v233 offset:47104
	ds_read_b64_tr_b16 v[100:101], v233 offset:47616
	s_waitcnt lgkmcnt(14)
	v_mfma_f32_32x32x16_bf16 v[66:81], v[178:181], v[142:145], v[66:81]
	v_add_f32_e32 v65, v104, v65
	v_add_f32_e32 v65, v105, v65
	v_add_f32_e32 v65, v106, v65
	v_add_f32_e32 v65, v107, v65
	v_cvt_pk_bf16_f32 v140, v102, v103
	v_cvt_pk_bf16_f32 v141, v104, v105
	ds_read_b64_tr_b16 v[102:103], v233 offset:44032
	ds_read_b64_tr_b16 v[104:105], v233 offset:44544
	s_waitcnt lgkmcnt(14)
	v_mfma_f32_32x32x16_bf16 v[82:97], v[182:185], v[134:137], v[82:97]
	v_add_f32_e32 v65, v108, v65
	v_add_f32_e32 v65, v109, v65
	v_add_f32_e32 v65, v110, v65
	v_add_f32_e32 v65, v111, v65
	v_cvt_pk_bf16_f32 v130, v106, v107
	v_cvt_pk_bf16_f32 v131, v108, v109
	ds_read_b64_tr_b16 v[106:107], v233 offset:48128
	ds_read_b64_tr_b16 v[108:109], v233 offset:48640
	v_mfma_f32_32x32x16_bf16 v[66:81], v[52:55], v[134:137], v[66:81]
	v_add_f32_e32 v52, v112, v65
	v_add_f32_e32 v52, v113, v52
	v_cvt_pk_bf16_f32 v132, v110, v111
	v_cvt_pk_bf16_f32 v133, v112, v113
	s_mov_b32 m0, s18
	s_nop 0
	global_load_lds_dwordx4 v240, s[100:101]
	s_add_i32 m0, s19, 0x2000
	s_nop 0
	global_load_lds_dwordx4 v241, s[100:101]
	s_waitcnt lgkmcnt(14)
	v_mfma_f32_32x32x16_bf16 v[18:33], v[154:157], v[186:189], v[18:33]
	s_add_u32 s100, s100, 0x2000
	s_addc_u32 s101, s101, 0
	v_exp_f32_e32 v82, v82
	v_exp_f32_e32 v83, v83
	v_exp_f32_e32 v84, v84
	v_exp_f32_e32 v85, v85
	s_waitcnt lgkmcnt(12)
	v_mfma_f32_32x32x16_bf16 v[34:49], v[154:157], v[60:63], v[34:49]
	v_exp_f32_e32 v86, v86
	v_exp_f32_e32 v87, v87
	v_exp_f32_e32 v88, v88
	v_exp_f32_e32 v89, v89
	ds_read_b128 v[190:193], v230 offset:8192
	ds_read_b128 v[186:189], v230 offset:8704
	s_waitcnt lgkmcnt(12)
	v_mfma_f32_32x32x16_bf16 v[18:33], v[146:149], v[114:117], v[18:33]
	v_exp_f32_e32 v90, v90
	v_exp_f32_e32 v91, v91
	v_exp_f32_e32 v92, v92
	v_exp_f32_e32 v93, v93
	ds_read_b128 v[182:185], v230 offset:10240
	ds_read_b128 v[178:181], v230 offset:10752
	s_waitcnt lgkmcnt(12)
	v_mfma_f32_32x32x16_bf16 v[34:49], v[146:149], v[118:121], v[34:49]
	v_exp_f32_e32 v94, v94
	v_exp_f32_e32 v95, v95
	v_exp_f32_e32 v96, v96
	v_exp_f32_e32 v97, v97
	ds_read_b128 v[174:177], v230 offset:12288
	ds_read_b128 v[170:173], v230 offset:12800
	s_waitcnt lgkmcnt(12)
	v_mfma_f32_32x32x16_bf16 v[18:33], v[138:141], v[122:125], v[18:33]
	v_exp_f32_e32 v66, v66
	v_exp_f32_e32 v67, v67
	v_exp_f32_e32 v68, v68
	v_exp_f32_e32 v69, v69
	ds_read_b128 v[166:169], v230 offset:14336
	ds_read_b128 v[162:165], v230 offset:14848
	s_waitcnt lgkmcnt(12)
	v_mfma_f32_32x32x16_bf16 v[34:49], v[138:141], v[98:101], v[34:49]
	v_exp_f32_e32 v70, v70
	v_exp_f32_e32 v71, v71
	v_exp_f32_e32 v72, v72
	v_exp_f32_e32 v73, v73
	s_waitcnt lgkmcnt(10)
	v_mfma_f32_32x32x16_bf16 v[18:33], v[130:133], v[102:105], v[18:33]
	v_exp_f32_e32 v74, v74
	v_exp_f32_e32 v75, v75
	v_exp_f32_e32 v76, v76
	v_exp_f32_e32 v77, v77
	s_waitcnt lgkmcnt(8)
	v_mfma_f32_32x32x16_bf16 v[34:49], v[130:133], v[106:109], v[34:49]
	v_exp_f32_e32 v78, v78
	v_exp_f32_e32 v79, v79
	v_exp_f32_e32 v80, v80
	v_exp_f32_e32 v81, v81
	s_waitcnt vmcnt(2) lgkmcnt(0)
	s_barrier
	v_add_f32_e32 v50, v50, v51
	v_add_f32_e32 v50, v50, v52
	s_add_i32 s10, s10, 12
	s_add_i32 s5, s10, 10
	s_cmp_lt_u32 s5, s55
	s_cbranch_scc1 .Lattn6
	s_cmp_lt_u32 s10, s55
	s_cbranch_scc1 .LBB0_278
	s_mov_b32 s4, 0
	s_add_i32 s5, s10, -2
	s_branch .Lattn6_exit

; #define PG8_STAGE(bufoff, gbase, voff) do { _Pragma("unroll") for (int _i = 0; _i < 2; ++_i) \
;         __builtin_amdgcn_global_load_lds((const unsigned*)((const char*)(gbase) + (voff)[_i]), (PG8_LAS unsigned*)(lds + (bufoff) + ldsw + _i * 8192), 16, 0, 0); } while (0)
; #define PG8_LDA(dst, b, h) do { _Pragma("unroll") for (int m = 0; m < 4; ++m) _Pragma("unroll") for (int k = 0; k < 2; ++k) dst[m][k] = *(const PG8_LAS bf16x8*)(lds + PG8_SA(b, h) + aoff + m * 2048 + k * 1024); } while (0)
; #define PG8_LDB(dst, b, h) do { _Pragma("unroll") for (int n = 0; n < 2; ++n) _Pragma("unroll") for (int k = 0; k < 2; ++k) dst[n][k] = *(const PG8_LAS bf16x8*)(lds + PG8_SB(b, h) + boff + n * 2048 + k * 1024); } while (0)
; #define PG8_WAIT_V(n) asm volatile("s_waitcnt vmcnt(" #n ")" ::: "memory")
; #define PG8_WAIT_L(n) asm volatile("s_waitcnt lgkmcnt(" #n ")" ::: "memory")
; #define PG8_BAR __builtin_amdgcn_s_barrier()
; #define PG8_SCHED __builtin_amdgcn_sched_barrier(0)
; template <class Epi, class Sched, bool ALIGN_EPI = false, bool SP2 = false>
; __device__ __forceinline__ void gemm_phase(PG8_LAS unsigned char* lds, const Gemm g, const Sched& S, const Epi& E) {
;     ...
;         const bool has_next = S.next(ui + 1, nxt);
;         const char* nA = has_next ? (const char*)g.A + (size_t)nxt.pm * tstep : cA; const char* nB = has_next ? (const char*)g.Bt + (size_t)nxt.pn * tstep : cB;
;         for (int t = 0; t < nt; t += 2) {
;             const bool last = (t == nt - 2);
;             const char* a1 = cA + (size_t)(t + 1) * kstep;
;             const char* a2 = last ? nA : cA + (size_t)(t + 2) * kstep; const char* b2 = last ? nB : cB + (size_t)(t + 2) * kstep;
;             const char* a3 = a2 + kstep; const char* b3 = b2 + kstep;
;             if (last && has_next) S.a_ready(nxt);
;             if constexpr (SP2) {
;             PG8_LDB(B0, 0, 0); PG8_LDB(B1, 0, 1); PG8_SCHED; PG8_LDA(At, 0, 0); PG8_STAGE(PG8_SA(1, 1), a1 + hstep, voffA);
;             PG8_WAIT_V(8); PG8_WAIT_L(0); PG8_BAR; PG8_MMA(0, 0, At, B0); PG8_MMA(0, 1, At, B1); PG8_BAR; PG8_SCHED;
;             PG8_LDA(At, 0, 1); PG8_STAGE(PG8_SB(0, 0), b2, voffB); PG8_STAGE(PG8_SB(0, 1), b2 + hstep, voffB); PG8_STAGE(PG8_SA(0, 0), a2, voffA);
;             PG8_WAIT_V(8); PG8_WAIT_L(0); PG8_BAR; PG8_MMA(1, 0, At, B0); PG8_MMA(1, 1, At, B1); PG8_BAR; PG8_SCHED;
.LBB0_410:
	s_add_i32 vcc_hi, s28, 2
	s_add_u32 s86, s14, 0x80
	s_addc_u32 s29, s15, 0
	s_add_i32 s88, 0, 0x10000
	s_cmp_eq_u32 s83, s28
	s_cselect_b32 s29, s30, s29
	s_cselect_b32 s28, s31, s86
	s_cselect_b32 s87, s37, vcc_lo
	s_cselect_b32 s86, s45, s47
	s_add_i32 s89, 0, 0x14000
	v_add_u32_e32 v86, s88, v161
	v_add_u32_e32 v172, s89, v161
	ds_read_b128 v[74:77], v86
	ds_read_b128 v[78:81], v86 offset:1024
	ds_read_b128 v[82:85], v86 offset:2048
	ds_read_b128 v[86:89], v86 offset:3072
	ds_read_b128 v[156:159], v172
	ds_read_b128 v[164:167], v172 offset:1024
	ds_read_b128 v[168:171], v172 offset:2048
	ds_read_b128 v[172:175], v172 offset:3072
	v_lshl_add_u64 v[204:205], s[14:15], 0, v[152:153]
	s_add_i32 m0, s61, 0xc000
	ds_read_b128 v[176:179], v163
	ds_read_b128 v[180:183], v163 offset:1024
	ds_read_b128 v[184:187], v163 offset:2048
	ds_read_b128 v[188:191], v163 offset:3072
	ds_read_b128 v[192:195], v163 offset:4096
	ds_read_b128 v[196:199], v163 offset:5120
	ds_read_b128 v[200:203], v163 offset:6144
	ds_read_b128 v[210:213], v163 offset:7168
	global_load_lds_dwordx4 v[204:205], off
	v_lshl_add_u64 v[204:205], s[14:15], 0, v[154:155]
	s_add_i32 m0, s61, 0xe000
	s_nop 0
	global_load_lds_dwordx4 v[204:205], off
	s_waitcnt vmcnt(8)
	s_waitcnt lgkmcnt(0)
	s_barrier
	s_setprio 1
	s_waitcnt lgkmcnt(0)
	v_mfma_f32_16x16x32_bf16 v[142:145], v[74:77], v[176:179], v[142:145]
	v_mfma_f32_16x16x32_bf16 v[138:141], v[82:85], v[176:179], v[138:141]
	v_mfma_f32_16x16x32_bf16 v[126:129], v[74:77], v[184:187], v[126:129]
	v_mfma_f32_16x16x32_bf16 v[122:125], v[82:85], v[184:187], v[122:125]
	v_mfma_f32_16x16x32_bf16 v[110:113], v[74:77], v[192:195], v[110:113]
	v_mfma_f32_16x16x32_bf16 v[106:109], v[82:85], v[192:195], v[106:109]
	v_mfma_f32_16x16x32_bf16 v[94:97], v[74:77], v[200:203], v[94:97]
	v_mfma_f32_16x16x32_bf16 v[90:93], v[82:85], v[200:203], v[90:93]
	v_mfma_f32_16x16x32_bf16 v[142:145], v[78:81], v[180:183], v[142:145]
	v_mfma_f32_16x16x32_bf16 v[138:141], v[86:89], v[180:183], v[138:141]
	v_mfma_f32_16x16x32_bf16 v[126:129], v[78:81], v[188:191], v[126:129]
	v_mfma_f32_16x16x32_bf16 v[122:125], v[86:89], v[188:191], v[122:125]
	v_mfma_f32_16x16x32_bf16 v[110:113], v[78:81], v[196:199], v[110:113]
	v_mfma_f32_16x16x32_bf16 v[106:109], v[86:89], v[196:199], v[106:109]
	v_mfma_f32_16x16x32_bf16 v[94:97], v[78:81], v[210:213], v[94:97]
	v_mfma_f32_16x16x32_bf16 v[90:93], v[86:89], v[210:213], v[90:93]
	s_setprio 0
	s_setprio 1
	v_mfma_f32_16x16x32_bf16 v[134:137], v[156:159], v[176:179], v[134:137]
	v_mfma_f32_16x16x32_bf16 v[130:133], v[168:171], v[176:179], v[130:133]
	v_mfma_f32_16x16x32_bf16 v[118:121], v[156:159], v[184:187], v[118:121]
	v_mfma_f32_16x16x32_bf16 v[114:117], v[168:171], v[184:187], v[114:117]
	v_mfma_f32_16x16x32_bf16 v[102:105], v[156:159], v[192:195], v[102:105]
	v_mfma_f32_16x16x32_bf16 v[98:101], v[168:171], v[192:195], v[98:101]
	v_mfma_f32_16x16x32_bf16 v[70:73], v[156:159], v[200:203], v[70:73]
	v_mfma_f32_16x16x32_bf16 v[66:69], v[168:171], v[200:203], v[66:69]
	v_mfma_f32_16x16x32_bf16 v[134:137], v[164:167], v[180:183], v[134:137]
	v_mfma_f32_16x16x32_bf16 v[130:133], v[172:175], v[180:183], v[130:133]
	v_mfma_f32_16x16x32_bf16 v[118:121], v[164:167], v[188:191], v[118:121]
	v_mfma_f32_16x16x32_bf16 v[114:117], v[172:175], v[188:191], v[114:117]
	v_mfma_f32_16x16x32_bf16 v[102:105], v[164:167], v[196:199], v[102:105]
	v_mfma_f32_16x16x32_bf16 v[98:101], v[172:175], v[196:199], v[98:101]
	v_mfma_f32_16x16x32_bf16 v[70:73], v[164:167], v[210:213], v[70:73]
	v_mfma_f32_16x16x32_bf16 v[66:69], v[172:175], v[210:213], v[66:69]
	s_setprio 0
	s_barrier
	s_add_i32 s88, s88, s62
	v_lshl_add_u64 v[204:205], s[86:87], 0, v[0:1]
	s_mov_b32 m0, s88
	ds_read_b128 v[176:179], v163 offset:16384
	ds_read_b128 v[180:183], v163 offset:17408
	ds_read_b128 v[184:187], v163 offset:18432
	ds_read_b128 v[188:191], v163 offset:19456
	ds_read_b128 v[192:195], v163 offset:20480
	ds_read_b128 v[196:199], v163 offset:21504
	ds_read_b128 v[200:203], v163 offset:22528
	ds_read_b128 v[210:213], v163 offset:23552
	global_load_lds_dwordx4 v[204:205], off
	s_add_i32 m0, s88, 0x2000
	v_lshl_add_u64 v[226:227], s[86:87], 0, v[150:151]
	s_add_u32 s86, s86, s10
	s_addc_u32 s87, s87, 0
	s_add_i32 s88, s89, s62
	global_load_lds_dwordx4 v[226:227], off
	v_lshl_add_u64 v[228:229], s[86:87], 0, v[0:1]
	s_mov_b32 m0, s88
	v_lshl_add_u64 v[230:231], s[86:87], 0, v[150:151]
	global_load_lds_dwordx4 v[228:229], off
	s_add_i32 m0, s88, 0x2000
	v_lshl_add_u64 v[232:233], s[28:29], 0, v[146:147]
	global_load_lds_dwordx4 v[230:231], off
	s_mov_b32 m0, s61
	v_lshl_add_u64 v[234:235], s[28:29], 0, v[148:149]
	global_load_lds_dwordx4 v[232:233], off
	s_mov_b32 m0, s77
	s_nop 0
	global_load_lds_dwordx4 v[234:235], off
	s_waitcnt vmcnt(8)
	s_waitcnt lgkmcnt(0)
	s_barrier
; #define PG8_STAGE(bufoff, gbase, voff) do { _Pragma("unroll") for (int _i = 0; _i < 2; ++_i) \
;         __builtin_amdgcn_global_load_lds((const unsigned*)((const char*)(gbase) + (voff)[_i]), (PG8_LAS unsigned*)(lds + (bufoff) + ldsw + _i * 8192), 16, 0, 0); } while (0)
; #define PG8_LDA(dst, b, h) do { _Pragma("unroll") for (int m = 0; m < 4; ++m) _Pragma("unroll") for (int k = 0; k < 2; ++k) dst[m][k] = *(const PG8_LAS bf16x8*)(lds + PG8_SA(b, h) + aoff + m * 2048 + k * 1024); } while (0)
; #define PG8_LDB(dst, b, h) do { _Pragma("unroll") for (int n = 0; n < 2; ++n) _Pragma("unroll") for (int k = 0; k < 2; ++k) dst[n][k] = *(const PG8_LAS bf16x8*)(lds + PG8_SB(b, h) + boff + n * 2048 + k * 1024); } while (0)
; #define PG8_MMA(ai, bj, At, Bt) do { __builtin_amdgcn_s_setprio(1); _Pragma("unroll") for (int m = 0; m < 4; ++m) _Pragma("unroll") for (int n = 0; n < 2; ++n) _Pragma("unroll") for (int k = 0; k < 2; ++k) \
;         acc[ai][bj][m][n] = __builtin_amdgcn_mfma_f32_16x16x32_bf16(Bt[n][k], At[m][k], acc[ai][bj][m][n], 0, 0, 0); __builtin_amdgcn_s_setprio(0); } while (0)
; #define PG8_WAIT_V(n) asm volatile("s_waitcnt vmcnt(" #n ")" ::: "memory")
; #define PG8_WAIT_L(n) asm volatile("s_waitcnt lgkmcnt(" #n ")" ::: "memory")
; #define PG8_BAR __builtin_amdgcn_s_barrier()
; #define PG8_SCHED __builtin_amdgcn_sched_barrier(0)
; template <class Epi, class Sched, bool ALIGN_EPI = false, bool SP2 = false>
; __device__ __forceinline__ void gemm_phase(PG8_LAS unsigned char* lds, const Gemm g, const Sched& S, const Epi& E) {
;     ...
;             PG8_WAIT_V(8); PG8_WAIT_L(0); PG8_BAR; PG8_MMA(1, 0, At, B0); PG8_MMA(1, 1, At, B1); PG8_BAR; PG8_SCHED;
;             PG8_LDB(B0, 1, 0); PG8_LDB(B1, 1, 1); PG8_SCHED; PG8_LDA(At, 1, 0); PG8_STAGE(PG8_SA(0, 1), a2 + hstep, voffA);
;             PG8_WAIT_V(8); PG8_WAIT_L(0); PG8_BAR; PG8_MMA(0, 0, At, B0); PG8_MMA(0, 1, At, B1); PG8_BAR; PG8_SCHED;
;             PG8_LDA(At, 1, 1); PG8_STAGE(PG8_SB(1, 0), b3, voffB); PG8_STAGE(PG8_SB(1, 1), b3 + hstep, voffB); PG8_STAGE(PG8_SA(1, 0), a3, voffA);
	s_setprio 1
	s_waitcnt lgkmcnt(0)
	v_mfma_f32_16x16x32_bf16 v[62:65], v[74:77], v[176:179], v[62:65]
	v_mfma_f32_16x16x32_bf16 v[58:61], v[82:85], v[176:179], v[58:61]
	v_mfma_f32_16x16x32_bf16 v[46:49], v[74:77], v[184:187], v[46:49]
	v_mfma_f32_16x16x32_bf16 v[42:45], v[82:85], v[184:187], v[42:45]
	v_mfma_f32_16x16x32_bf16 v[30:33], v[74:77], v[192:195], v[30:33]
	v_mfma_f32_16x16x32_bf16 v[26:29], v[82:85], v[192:195], v[26:29]
	v_mfma_f32_16x16x32_bf16 v[14:17], v[74:77], v[200:203], v[14:17]
	v_mfma_f32_16x16x32_bf16 v[10:13], v[82:85], v[200:203], v[10:13]
	v_mfma_f32_16x16x32_bf16 v[62:65], v[78:81], v[180:183], v[62:65]
	v_mfma_f32_16x16x32_bf16 v[58:61], v[86:89], v[180:183], v[58:61]
	v_mfma_f32_16x16x32_bf16 v[46:49], v[78:81], v[188:191], v[46:49]
	v_mfma_f32_16x16x32_bf16 v[42:45], v[86:89], v[188:191], v[42:45]
	v_mfma_f32_16x16x32_bf16 v[30:33], v[78:81], v[196:199], v[30:33]
	v_mfma_f32_16x16x32_bf16 v[26:29], v[86:89], v[196:199], v[26:29]
	v_mfma_f32_16x16x32_bf16 v[14:17], v[78:81], v[210:213], v[14:17]
	v_mfma_f32_16x16x32_bf16 v[10:13], v[86:89], v[210:213], v[10:13]
	s_setprio 0
	s_setprio 1
	v_mfma_f32_16x16x32_bf16 v[54:57], v[156:159], v[176:179], v[54:57]
	v_mfma_f32_16x16x32_bf16 v[50:53], v[168:171], v[176:179], v[50:53]
	v_mfma_f32_16x16x32_bf16 v[38:41], v[156:159], v[184:187], v[38:41]
	v_mfma_f32_16x16x32_bf16 v[34:37], v[168:171], v[184:187], v[34:37]
	v_mfma_f32_16x16x32_bf16 v[22:25], v[156:159], v[192:195], v[22:25]
	v_mfma_f32_16x16x32_bf16 v[18:21], v[168:171], v[192:195], v[18:21]
	v_mfma_f32_16x16x32_bf16 v[6:9], v[156:159], v[200:203], v[6:9]
	v_mfma_f32_16x16x32_bf16 v[2:5], v[168:171], v[200:203], v[2:5]
	v_mfma_f32_16x16x32_bf16 v[54:57], v[164:167], v[180:183], v[54:57]
	v_mfma_f32_16x16x32_bf16 v[50:53], v[172:175], v[180:183], v[50:53]
	v_mfma_f32_16x16x32_bf16 v[38:41], v[164:167], v[188:191], v[38:41]
	v_mfma_f32_16x16x32_bf16 v[34:37], v[172:175], v[188:191], v[34:37]
	v_mfma_f32_16x16x32_bf16 v[22:25], v[164:167], v[196:199], v[22:25]
	v_mfma_f32_16x16x32_bf16 v[18:21], v[172:175], v[196:199], v[18:21]
	v_mfma_f32_16x16x32_bf16 v[6:9], v[164:167], v[210:213], v[6:9]
	v_mfma_f32_16x16x32_bf16 v[2:5], v[172:175], v[210:213], v[2:5]
	s_setprio 0
	s_barrier
	s_add_i32 s86, 0, 0x18000
	s_add_i32 s87, 0, 0x1c000
	v_add_u32_e32 v86, s86, v161
	v_add_u32_e32 v172, s87, v161
	ds_read_b128 v[74:77], v86
	ds_read_b128 v[78:81], v86 offset:1024
	ds_read_b128 v[82:85], v86 offset:2048
	ds_read_b128 v[86:89], v86 offset:3072
	ds_read_b128 v[156:159], v172
	ds_read_b128 v[164:167], v172 offset:1024
	ds_read_b128 v[168:171], v172 offset:2048
	ds_read_b128 v[172:175], v172 offset:3072
	s_add_u32 s28, s28, s10
	s_addc_u32 s29, s29, 0
	s_mov_b32 m0, s78
	v_lshl_add_u64 v[236:237], s[28:29], 0, v[146:147]
	ds_read_b128 v[176:179], v163 offset:32768
	ds_read_b128 v[180:183], v163 offset:33792
	ds_read_b128 v[184:187], v163 offset:34816
	ds_read_b128 v[188:191], v163 offset:35840
	ds_read_b128 v[192:195], v163 offset:36864
	ds_read_b128 v[196:199], v163 offset:37888
	ds_read_b128 v[200:203], v163 offset:38912
	ds_read_b128 v[210:213], v163 offset:39936
	global_load_lds_dwordx4 v[236:237], off
	v_lshl_add_u64 v[236:237], s[28:29], 0, v[148:149]
	s_mov_b32 m0, s79
	s_nop 0
	global_load_lds_dwordx4 v[236:237], off
	s_waitcnt vmcnt(8)
	s_waitcnt lgkmcnt(0)
	s_barrier
	s_setprio 1
	s_waitcnt lgkmcnt(0)
	v_mfma_f32_16x16x32_bf16 v[142:145], v[74:77], v[176:179], v[142:145]
	v_mfma_f32_16x16x32_bf16 v[138:141], v[82:85], v[176:179], v[138:141]
	v_mfma_f32_16x16x32_bf16 v[126:129], v[74:77], v[184:187], v[126:129]
	v_mfma_f32_16x16x32_bf16 v[122:125], v[82:85], v[184:187], v[122:125]
	v_mfma_f32_16x16x32_bf16 v[110:113], v[74:77], v[192:195], v[110:113]
	v_mfma_f32_16x16x32_bf16 v[106:109], v[82:85], v[192:195], v[106:109]
	v_mfma_f32_16x16x32_bf16 v[94:97], v[74:77], v[200:203], v[94:97]
	v_mfma_f32_16x16x32_bf16 v[90:93], v[82:85], v[200:203], v[90:93]
	v_mfma_f32_16x16x32_bf16 v[142:145], v[78:81], v[180:183], v[142:145]
	v_mfma_f32_16x16x32_bf16 v[138:141], v[86:89], v[180:183], v[138:141]
	v_mfma_f32_16x16x32_bf16 v[126:129], v[78:81], v[188:191], v[126:129]
	v_mfma_f32_16x16x32_bf16 v[122:125], v[86:89], v[188:191], v[122:125]
	v_mfma_f32_16x16x32_bf16 v[110:113], v[78:81], v[196:199], v[110:113]
	v_mfma_f32_16x16x32_bf16 v[106:109], v[86:89], v[196:199], v[106:109]
	v_mfma_f32_16x16x32_bf16 v[94:97], v[78:81], v[210:213], v[94:97]
	v_mfma_f32_16x16x32_bf16 v[90:93], v[86:89], v[210:213], v[90:93]
	s_setprio 0
	s_setprio 1
	v_mfma_f32_16x16x32_bf16 v[134:137], v[156:159], v[176:179], v[134:137]
	v_mfma_f32_16x16x32_bf16 v[130:133], v[168:171], v[176:179], v[130:133]
	v_mfma_f32_16x16x32_bf16 v[118:121], v[156:159], v[184:187], v[118:121]
	v_mfma_f32_16x16x32_bf16 v[114:117], v[168:171], v[184:187], v[114:117]
	v_mfma_f32_16x16x32_bf16 v[102:105], v[156:159], v[192:195], v[102:105]
	v_mfma_f32_16x16x32_bf16 v[98:101], v[168:171], v[192:195], v[98:101]
	v_mfma_f32_16x16x32_bf16 v[70:73], v[156:159], v[200:203], v[70:73]
	v_mfma_f32_16x16x32_bf16 v[66:69], v[168:171], v[200:203], v[66:69]
	v_mfma_f32_16x16x32_bf16 v[134:137], v[164:167], v[180:183], v[134:137]
	v_mfma_f32_16x16x32_bf16 v[130:133], v[172:175], v[180:183], v[130:133]
	v_mfma_f32_16x16x32_bf16 v[118:121], v[164:167], v[188:191], v[118:121]
	v_mfma_f32_16x16x32_bf16 v[114:117], v[172:175], v[188:191], v[114:117]
	v_mfma_f32_16x16x32_bf16 v[102:105], v[164:167], v[196:199], v[102:105]
	v_mfma_f32_16x16x32_bf16 v[98:101], v[172:175], v[196:199], v[98:101]
	v_mfma_f32_16x16x32_bf16 v[70:73], v[164:167], v[210:213], v[70:73]
	v_mfma_f32_16x16x32_bf16 v[66:69], v[172:175], v[210:213], v[66:69]
	s_setprio 0
	s_barrier
; #define PG8_STAGE(bufoff, gbase, voff) do { _Pragma("unroll") for (int _i = 0; _i < 2; ++_i) \
;         __builtin_amdgcn_global_load_lds((const unsigned*)((const char*)(gbase) + (voff)[_i]), (PG8_LAS unsigned*)(lds + (bufoff) + ldsw + _i * 8192), 16, 0, 0); } while (0)
; #define PG8_LDA(dst, b, h) do { _Pragma("unroll") for (int m = 0; m < 4; ++m) _Pragma("unroll") for (int k = 0; k < 2; ++k) dst[m][k] = *(const PG8_LAS bf16x8*)(lds + PG8_SA(b, h) + aoff + m * 2048 + k * 1024); } while (0)
; #define PG8_LDB(dst, b, h) do { _Pragma("unroll") for (int n = 0; n < 2; ++n) _Pragma("unroll") for (int k = 0; k < 2; ++k) dst[n][k] = *(const PG8_LAS bf16x8*)(lds + PG8_SB(b, h) + boff + n * 2048 + k * 1024); } while (0)
; #define PG8_MMA(ai, bj, At, Bt) do { __builtin_amdgcn_s_setprio(1); _Pragma("unroll") for (int m = 0; m < 4; ++m) _Pragma("unroll") for (int n = 0; n < 2; ++n) _Pragma("unroll") for (int k = 0; k < 2; ++k) \
;         acc[ai][bj][m][n] = __builtin_amdgcn_mfma_f32_16x16x32_bf16(Bt[n][k], At[m][k], acc[ai][bj][m][n], 0, 0, 0); __builtin_amdgcn_s_setprio(0); } while (0)
; #define PG8_WAIT_V(n) asm volatile("s_waitcnt vmcnt(" #n ")" ::: "memory")
; #define PG8_WAIT_L(n) asm volatile("s_waitcnt lgkmcnt(" #n ")" ::: "memory")
; #define PG8_BAR __builtin_amdgcn_s_barrier()
; #define PG8_SCHED __builtin_amdgcn_sched_barrier(0)
; template <class Epi, class Sched, bool ALIGN_EPI = false, bool SP2 = false>
; __device__ __forceinline__ void gemm_phase(PG8_LAS unsigned char* lds, const Gemm g, const Sched& S, const Epi& E) {
;     ...
;             const bool last = (t == nt - 2);
;             const char* a1 = cA + (size_t)(t + 1) * kstep;
;             const char* a2 = last ? nA : cA + (size_t)(t + 2) * kstep; const char* b2 = last ? nB : cB + (size_t)(t + 2) * kstep;
;             const char* a3 = a2 + kstep; const char* b3 = b2 + kstep;
;             if (last && has_next) S.a_ready(nxt);
;             if constexpr (SP2) {
;             PG8_LDB(B0, 0, 0); PG8_LDB(B1, 0, 1); PG8_SCHED; PG8_LDA(At, 0, 0); PG8_STAGE(PG8_SA(1, 1), a1 + hstep, voffA);
;     ...
;             PG8_LDA(At, 1, 1); PG8_STAGE(PG8_SB(1, 0), b3, voffB); PG8_STAGE(PG8_SB(1, 1), b3 + hstep, voffB); PG8_STAGE(PG8_SA(1, 0), a3, voffA);
;             PG8_WAIT_V(8); PG8_WAIT_L(0); PG8_BAR; PG8_MMA(1, 0, At, B0); PG8_MMA(1, 1, At, B1); PG8_BAR; PG8_SCHED;
	s_add_i32 s28, s86, s62
	v_lshl_add_u64 v[204:205], v[204:205], 0, s[24:25]
	s_mov_b32 m0, s28
	ds_read_b128 v[176:179], v163 offset:49152
	ds_read_b128 v[180:183], v163 offset:50176
	ds_read_b128 v[184:187], v163 offset:51200
	ds_read_b128 v[188:191], v163 offset:52224
	ds_read_b128 v[192:195], v163 offset:53248
	ds_read_b128 v[196:199], v163 offset:54272
	ds_read_b128 v[200:203], v163 offset:55296
	ds_read_b128 v[210:213], v163 offset:56320
	global_load_lds_dwordx4 v[204:205], off
	v_lshl_add_u64 v[204:205], v[226:227], 0, s[24:25]
	s_add_i32 m0, s28, 0x2000
	s_add_i32 s28, s87, s62
	global_load_lds_dwordx4 v[204:205], off
	v_lshl_add_u64 v[204:205], v[228:229], 0, s[24:25]
	s_mov_b32 m0, s28
	s_nop 0
	global_load_lds_dwordx4 v[204:205], off
	v_lshl_add_u64 v[204:205], v[230:231], 0, s[24:25]
	s_add_i32 m0, s28, 0x2000
	s_nop 0
	global_load_lds_dwordx4 v[204:205], off
	v_lshl_add_u64 v[204:205], v[232:233], 0, s[24:25]
	s_mov_b32 m0, s80
	s_nop 0
	global_load_lds_dwordx4 v[204:205], off
	v_lshl_add_u64 v[204:205], v[234:235], 0, s[24:25]
	s_mov_b32 m0, s81
	s_nop 0
	global_load_lds_dwordx4 v[204:205], off
	s_waitcnt vmcnt(8)
	s_waitcnt lgkmcnt(0)
	s_barrier
	s_setprio 1
	s_waitcnt lgkmcnt(0)
	v_mfma_f32_16x16x32_bf16 v[62:65], v[74:77], v[176:179], v[62:65]
	v_mfma_f32_16x16x32_bf16 v[58:61], v[82:85], v[176:179], v[58:61]
	v_mfma_f32_16x16x32_bf16 v[46:49], v[74:77], v[184:187], v[46:49]
	v_mfma_f32_16x16x32_bf16 v[42:45], v[82:85], v[184:187], v[42:45]
	v_mfma_f32_16x16x32_bf16 v[30:33], v[74:77], v[192:195], v[30:33]
	v_mfma_f32_16x16x32_bf16 v[26:29], v[82:85], v[192:195], v[26:29]
	v_mfma_f32_16x16x32_bf16 v[14:17], v[74:77], v[200:203], v[14:17]
	v_mfma_f32_16x16x32_bf16 v[10:13], v[82:85], v[200:203], v[10:13]
	v_mfma_f32_16x16x32_bf16 v[62:65], v[78:81], v[180:183], v[62:65]
	v_mfma_f32_16x16x32_bf16 v[58:61], v[86:89], v[180:183], v[58:61]
	v_mfma_f32_16x16x32_bf16 v[46:49], v[78:81], v[188:191], v[46:49]
	v_mfma_f32_16x16x32_bf16 v[42:45], v[86:89], v[188:191], v[42:45]
	v_mfma_f32_16x16x32_bf16 v[30:33], v[78:81], v[196:199], v[30:33]
	v_mfma_f32_16x16x32_bf16 v[26:29], v[86:89], v[196:199], v[26:29]
	v_mfma_f32_16x16x32_bf16 v[14:17], v[78:81], v[210:213], v[14:17]
	v_mfma_f32_16x16x32_bf16 v[10:13], v[86:89], v[210:213], v[10:13]
	s_setprio 0
	s_setprio 1
	v_mfma_f32_16x16x32_bf16 v[54:57], v[156:159], v[176:179], v[54:57]
	v_mfma_f32_16x16x32_bf16 v[50:53], v[168:171], v[176:179], v[50:53]
	v_mfma_f32_16x16x32_bf16 v[38:41], v[156:159], v[184:187], v[38:41]
	v_mfma_f32_16x16x32_bf16 v[34:37], v[168:171], v[184:187], v[34:37]
	v_mfma_f32_16x16x32_bf16 v[22:25], v[156:159], v[192:195], v[22:25]
	v_mfma_f32_16x16x32_bf16 v[18:21], v[168:171], v[192:195], v[18:21]
	v_mfma_f32_16x16x32_bf16 v[6:9], v[156:159], v[200:203], v[6:9]
	v_mfma_f32_16x16x32_bf16 v[2:5], v[168:171], v[200:203], v[2:5]
	v_mfma_f32_16x16x32_bf16 v[54:57], v[164:167], v[180:183], v[54:57]
	v_mfma_f32_16x16x32_bf16 v[50:53], v[172:175], v[180:183], v[50:53]
	v_mfma_f32_16x16x32_bf16 v[38:41], v[164:167], v[188:191], v[38:41]
	v_mfma_f32_16x16x32_bf16 v[34:37], v[172:175], v[188:191], v[34:37]
	v_mfma_f32_16x16x32_bf16 v[22:25], v[164:167], v[196:199], v[22:25]
	v_mfma_f32_16x16x32_bf16 v[18:21], v[172:175], v[196:199], v[18:21]
	v_mfma_f32_16x16x32_bf16 v[6:9], v[164:167], v[210:213], v[6:9]
	v_mfma_f32_16x16x32_bf16 v[2:5], v[172:175], v[210:213], v[2:5]
	s_setprio 0
	s_barrier
	s_add_u32 s14, s14, 0x100
	s_addc_u32 s15, s15, 0
	s_add_u32 s47, s47, 0x100
	s_addc_u32 vcc_lo, vcc_lo, 0
	s_mov_b32 s28, vcc_hi
	s_add_i32 vcc_hi, s28, 2
	s_add_u32 s86, s14, 0x80
	s_addc_u32 s29, s15, 0
	s_add_i32 s88, 0, 0x10000
	s_cmp_eq_u32 s83, s28
	s_cselect_b32 s29, s30, s29
	s_cselect_b32 s28, s31, s86
	s_cselect_b32 s87, s37, vcc_lo
	s_cselect_b32 s86, s45, s47
	s_add_i32 s89, 0, 0x14000
	v_add_u32_e32 v86, s88, v161
	v_add_u32_e32 v172, s89, v161
	ds_read_b128 v[74:77], v86
	ds_read_b128 v[78:81], v86 offset:1024
	ds_read_b128 v[82:85], v86 offset:2048
	ds_read_b128 v[86:89], v86 offset:3072
	ds_read_b128 v[156:159], v172
	ds_read_b128 v[164:167], v172 offset:1024
	ds_read_b128 v[168:171], v172 offset:2048
	ds_read_b128 v[172:175], v172 offset:3072
	v_lshl_add_u64 v[204:205], s[14:15], 0, v[152:153]
	s_add_i32 m0, s61, 0xc000
	ds_read_b128 v[176:179], v163
	ds_read_b128 v[180:183], v163 offset:1024
	ds_read_b128 v[184:187], v163 offset:2048
	ds_read_b128 v[188:191], v163 offset:3072
	ds_read_b128 v[192:195], v163 offset:4096
	ds_read_b128 v[196:199], v163 offset:5120
	ds_read_b128 v[200:203], v163 offset:6144
	ds_read_b128 v[210:213], v163 offset:7168
	global_load_lds_dwordx4 v[204:205], off
	v_lshl_add_u64 v[204:205], s[14:15], 0, v[154:155]
	s_add_i32 m0, s61, 0xe000
	s_nop 0
	global_load_lds_dwordx4 v[204:205], off
	s_waitcnt vmcnt(8)
	s_waitcnt lgkmcnt(0)
	s_barrier
; #define PG8_STAGE(bufoff, gbase, voff) do { _Pragma("unroll") for (int _i = 0; _i < 2; ++_i) \
;         __builtin_amdgcn_global_load_lds((const unsigned*)((const char*)(gbase) + (voff)[_i]), (PG8_LAS unsigned*)(lds + (bufoff) + ldsw + _i * 8192), 16, 0, 0); } while (0)
; #define PG8_LDA(dst, b, h) do { _Pragma("unroll") for (int m = 0; m < 4; ++m) _Pragma("unroll") for (int k = 0; k < 2; ++k) dst[m][k] = *(const PG8_LAS bf16x8*)(lds + PG8_SA(b, h) + aoff + m * 2048 + k * 1024); } while (0)
; #define PG8_MMA(ai, bj, At, Bt) do { __builtin_amdgcn_s_setprio(1); _Pragma("unroll") for (int m = 0; m < 4; ++m) _Pragma("unroll") for (int n = 0; n < 2; ++n) _Pragma("unroll") for (int k = 0; k < 2; ++k) \
;         acc[ai][bj][m][n] = __builtin_amdgcn_mfma_f32_16x16x32_bf16(Bt[n][k], At[m][k], acc[ai][bj][m][n], 0, 0, 0); __builtin_amdgcn_s_setprio(0); } while (0)
; #define PG8_WAIT_V(n) asm volatile("s_waitcnt vmcnt(" #n ")" ::: "memory")
; #define PG8_WAIT_L(n) asm volatile("s_waitcnt lgkmcnt(" #n ")" ::: "memory")
; #define PG8_BAR __builtin_amdgcn_s_barrier()
; #define PG8_SCHED __builtin_amdgcn_sched_barrier(0)
; template <class Epi, class Sched, bool ALIGN_EPI = false, bool SP2 = false>
; __device__ __forceinline__ void gemm_phase(PG8_LAS unsigned char* lds, const Gemm g, const Sched& S, const Epi& E) {
;     ...
;             PG8_WAIT_V(8); PG8_WAIT_L(0); PG8_BAR; PG8_MMA(0, 0, At, B0); PG8_MMA(0, 1, At, B1); PG8_BAR; PG8_SCHED;
;             PG8_LDA(At, 0, 1); PG8_STAGE(PG8_SB(0, 0), b2, voffB); PG8_STAGE(PG8_SB(0, 1), b2 + hstep, voffB); PG8_STAGE(PG8_SA(0, 0), a2, voffA);
;             PG8_WAIT_V(8); PG8_WAIT_L(0); PG8_BAR; PG8_MMA(1, 0, At, B0); PG8_MMA(1, 1, At, B1); PG8_BAR; PG8_SCHED;
	s_setprio 1
	s_waitcnt lgkmcnt(0)
	v_mfma_f32_16x16x32_bf16 v[142:145], v[74:77], v[176:179], v[142:145]
	v_mfma_f32_16x16x32_bf16 v[138:141], v[82:85], v[176:179], v[138:141]
	v_mfma_f32_16x16x32_bf16 v[126:129], v[74:77], v[184:187], v[126:129]
	v_mfma_f32_16x16x32_bf16 v[122:125], v[82:85], v[184:187], v[122:125]
	v_mfma_f32_16x16x32_bf16 v[110:113], v[74:77], v[192:195], v[110:113]
	v_mfma_f32_16x16x32_bf16 v[106:109], v[82:85], v[192:195], v[106:109]
	v_mfma_f32_16x16x32_bf16 v[94:97], v[74:77], v[200:203], v[94:97]
	v_mfma_f32_16x16x32_bf16 v[90:93], v[82:85], v[200:203], v[90:93]
	v_mfma_f32_16x16x32_bf16 v[142:145], v[78:81], v[180:183], v[142:145]
	v_mfma_f32_16x16x32_bf16 v[138:141], v[86:89], v[180:183], v[138:141]
	v_mfma_f32_16x16x32_bf16 v[126:129], v[78:81], v[188:191], v[126:129]
	v_mfma_f32_16x16x32_bf16 v[122:125], v[86:89], v[188:191], v[122:125]
	v_mfma_f32_16x16x32_bf16 v[110:113], v[78:81], v[196:199], v[110:113]
	v_mfma_f32_16x16x32_bf16 v[106:109], v[86:89], v[196:199], v[106:109]
	v_mfma_f32_16x16x32_bf16 v[94:97], v[78:81], v[210:213], v[94:97]
	v_mfma_f32_16x16x32_bf16 v[90:93], v[86:89], v[210:213], v[90:93]
	s_setprio 0
	s_setprio 1
	v_mfma_f32_16x16x32_bf16 v[134:137], v[156:159], v[176:179], v[134:137]
	v_mfma_f32_16x16x32_bf16 v[130:133], v[168:171], v[176:179], v[130:133]
	v_mfma_f32_16x16x32_bf16 v[118:121], v[156:159], v[184:187], v[118:121]
	v_mfma_f32_16x16x32_bf16 v[114:117], v[168:171], v[184:187], v[114:117]
	v_mfma_f32_16x16x32_bf16 v[102:105], v[156:159], v[192:195], v[102:105]
	v_mfma_f32_16x16x32_bf16 v[98:101], v[168:171], v[192:195], v[98:101]
	v_mfma_f32_16x16x32_bf16 v[70:73], v[156:159], v[200:203], v[70:73]
	v_mfma_f32_16x16x32_bf16 v[66:69], v[168:171], v[200:203], v[66:69]
	v_mfma_f32_16x16x32_bf16 v[134:137], v[164:167], v[180:183], v[134:137]
	v_mfma_f32_16x16x32_bf16 v[130:133], v[172:175], v[180:183], v[130:133]
	v_mfma_f32_16x16x32_bf16 v[118:121], v[164:167], v[188:191], v[118:121]
	v_mfma_f32_16x16x32_bf16 v[114:117], v[172:175], v[188:191], v[114:117]
	v_mfma_f32_16x16x32_bf16 v[102:105], v[164:167], v[196:199], v[102:105]
	v_mfma_f32_16x16x32_bf16 v[98:101], v[172:175], v[196:199], v[98:101]
	v_mfma_f32_16x16x32_bf16 v[70:73], v[164:167], v[210:213], v[70:73]
	v_mfma_f32_16x16x32_bf16 v[66:69], v[172:175], v[210:213], v[66:69]
	s_setprio 0
	s_barrier
	s_add_i32 s88, s88, s62
	v_lshl_add_u64 v[204:205], s[86:87], 0, v[0:1]
	s_mov_b32 m0, s88
	ds_read_b128 v[176:179], v163 offset:16384
	ds_read_b128 v[180:183], v163 offset:17408
	ds_read_b128 v[184:187], v163 offset:18432
	ds_read_b128 v[188:191], v163 offset:19456
	ds_read_b128 v[192:195], v163 offset:20480
	ds_read_b128 v[196:199], v163 offset:21504
	ds_read_b128 v[200:203], v163 offset:22528
	ds_read_b128 v[210:213], v163 offset:23552
	global_load_lds_dwordx4 v[204:205], off
	s_add_i32 m0, s88, 0x2000
	v_lshl_add_u64 v[226:227], s[86:87], 0, v[150:151]
	s_add_u32 s86, s86, s10
	s_addc_u32 s87, s87, 0
	s_add_i32 s88, s89, s62
	global_load_lds_dwordx4 v[226:227], off
	v_lshl_add_u64 v[228:229], s[86:87], 0, v[0:1]
	s_mov_b32 m0, s88
	v_lshl_add_u64 v[230:231], s[86:87], 0, v[150:151]
	global_load_lds_dwordx4 v[228:229], off
	s_add_i32 m0, s88, 0x2000
	v_lshl_add_u64 v[232:233], s[28:29], 0, v[146:147]
	global_load_lds_dwordx4 v[230:231], off
	s_mov_b32 m0, s61
	v_lshl_add_u64 v[234:235], s[28:29], 0, v[148:149]
	global_load_lds_dwordx4 v[232:233], off
	s_mov_b32 m0, s77
	s_nop 0
	global_load_lds_dwordx4 v[234:235], off
	s_waitcnt vmcnt(8)
	s_waitcnt lgkmcnt(0)
	s_barrier
	s_setprio 1
	s_waitcnt lgkmcnt(0)
	v_mfma_f32_16x16x32_bf16 v[62:65], v[74:77], v[176:179], v[62:65]
	v_mfma_f32_16x16x32_bf16 v[58:61], v[82:85], v[176:179], v[58:61]
	v_mfma_f32_16x16x32_bf16 v[46:49], v[74:77], v[184:187], v[46:49]
	v_mfma_f32_16x16x32_bf16 v[42:45], v[82:85], v[184:187], v[42:45]
	v_mfma_f32_16x16x32_bf16 v[30:33], v[74:77], v[192:195], v[30:33]
	v_mfma_f32_16x16x32_bf16 v[26:29], v[82:85], v[192:195], v[26:29]
	v_mfma_f32_16x16x32_bf16 v[14:17], v[74:77], v[200:203], v[14:17]
	v_mfma_f32_16x16x32_bf16 v[10:13], v[82:85], v[200:203], v[10:13]
	v_mfma_f32_16x16x32_bf16 v[62:65], v[78:81], v[180:183], v[62:65]
	v_mfma_f32_16x16x32_bf16 v[58:61], v[86:89], v[180:183], v[58:61]
	v_mfma_f32_16x16x32_bf16 v[46:49], v[78:81], v[188:191], v[46:49]
	v_mfma_f32_16x16x32_bf16 v[42:45], v[86:89], v[188:191], v[42:45]
	v_mfma_f32_16x16x32_bf16 v[30:33], v[78:81], v[196:199], v[30:33]
	v_mfma_f32_16x16x32_bf16 v[26:29], v[86:89], v[196:199], v[26:29]
	v_mfma_f32_16x16x32_bf16 v[14:17], v[78:81], v[210:213], v[14:17]
	v_mfma_f32_16x16x32_bf16 v[10:13], v[86:89], v[210:213], v[10:13]
	s_setprio 0
	s_setprio 1
	v_mfma_f32_16x16x32_bf16 v[54:57], v[156:159], v[176:179], v[54:57]
	v_mfma_f32_16x16x32_bf16 v[50:53], v[168:171], v[176:179], v[50:53]
	v_mfma_f32_16x16x32_bf16 v[38:41], v[156:159], v[184:187], v[38:41]
	v_mfma_f32_16x16x32_bf16 v[34:37], v[168:171], v[184:187], v[34:37]
	v_mfma_f32_16x16x32_bf16 v[22:25], v[156:159], v[192:195], v[22:25]
	v_mfma_f32_16x16x32_bf16 v[18:21], v[168:171], v[192:195], v[18:21]
	v_mfma_f32_16x16x32_bf16 v[6:9], v[156:159], v[200:203], v[6:9]
	v_mfma_f32_16x16x32_bf16 v[2:5], v[168:171], v[200:203], v[2:5]
	v_mfma_f32_16x16x32_bf16 v[54:57], v[164:167], v[180:183], v[54:57]
	v_mfma_f32_16x16x32_bf16 v[50:53], v[172:175], v[180:183], v[50:53]
	v_mfma_f32_16x16x32_bf16 v[38:41], v[164:167], v[188:191], v[38:41]
	v_mfma_f32_16x16x32_bf16 v[34:37], v[172:175], v[188:191], v[34:37]
	v_mfma_f32_16x16x32_bf16 v[22:25], v[164:167], v[196:199], v[22:25]
	v_mfma_f32_16x16x32_bf16 v[18:21], v[172:175], v[196:199], v[18:21]
	v_mfma_f32_16x16x32_bf16 v[6:9], v[164:167], v[210:213], v[6:9]
	v_mfma_f32_16x16x32_bf16 v[2:5], v[172:175], v[210:213], v[2:5]
	s_setprio 0
	s_barrier
; #define PG8_STAGE(bufoff, gbase, voff) do { _Pragma("unroll") for (int _i = 0; _i < 2; ++_i) \
;         __builtin_amdgcn_global_load_lds((const unsigned*)((const char*)(gbase) + (voff)[_i]), (PG8_LAS unsigned*)(lds + (bufoff) + ldsw + _i * 8192), 16, 0, 0); } while (0)
; #define PG8_LDA(dst, b, h) do { _Pragma("unroll") for (int m = 0; m < 4; ++m) _Pragma("unroll") for (int k = 0; k < 2; ++k) dst[m][k] = *(const PG8_LAS bf16x8*)(lds + PG8_SA(b, h) + aoff + m * 2048 + k * 1024); } while (0)
; #define PG8_LDB(dst, b, h) do { _Pragma("unroll") for (int n = 0; n < 2; ++n) _Pragma("unroll") for (int k = 0; k < 2; ++k) dst[n][k] = *(const PG8_LAS bf16x8*)(lds + PG8_SB(b, h) + boff + n * 2048 + k * 1024); } while (0)
; #define PG8_MMA(ai, bj, At, Bt) do { __builtin_amdgcn_s_setprio(1); _Pragma("unroll") for (int m = 0; m < 4; ++m) _Pragma("unroll") for (int n = 0; n < 2; ++n) _Pragma("unroll") for (int k = 0; k < 2; ++k) \
;         acc[ai][bj][m][n] = __builtin_amdgcn_mfma_f32_16x16x32_bf16(Bt[n][k], At[m][k], acc[ai][bj][m][n], 0, 0, 0); __builtin_amdgcn_s_setprio(0); } while (0)
; #define PG8_WAIT_V(n) asm volatile("s_waitcnt vmcnt(" #n ")" ::: "memory")
; #define PG8_WAIT_L(n) asm volatile("s_waitcnt lgkmcnt(" #n ")" ::: "memory")
; #define PG8_BAR __builtin_amdgcn_s_barrier()
; #define PG8_SCHED __builtin_amdgcn_sched_barrier(0)
; template <class Epi, class Sched, bool ALIGN_EPI = false, bool SP2 = false>
; __device__ __forceinline__ void gemm_phase(PG8_LAS unsigned char* lds, const Gemm g, const Sched& S, const Epi& E) {
;     ...
;             PG8_LDB(B0, 1, 0); PG8_LDB(B1, 1, 1); PG8_SCHED; PG8_LDA(At, 1, 0); PG8_STAGE(PG8_SA(0, 1), a2 + hstep, voffA);
;             PG8_WAIT_V(8); PG8_WAIT_L(0); PG8_BAR; PG8_MMA(0, 0, At, B0); PG8_MMA(0, 1, At, B1); PG8_BAR; PG8_SCHED;
	s_add_i32 s86, 0, 0x18000
	s_add_i32 s87, 0, 0x1c000
	v_add_u32_e32 v86, s86, v161
	v_add_u32_e32 v172, s87, v161
	ds_read_b128 v[74:77], v86
	ds_read_b128 v[78:81], v86 offset:1024
	ds_read_b128 v[82:85], v86 offset:2048
	ds_read_b128 v[86:89], v86 offset:3072
	ds_read_b128 v[156:159], v172
	ds_read_b128 v[164:167], v172 offset:1024
	ds_read_b128 v[168:171], v172 offset:2048
	ds_read_b128 v[172:175], v172 offset:3072
	s_add_u32 s28, s28, s10
	s_addc_u32 s29, s29, 0
	s_mov_b32 m0, s78
	v_lshl_add_u64 v[236:237], s[28:29], 0, v[146:147]
	ds_read_b128 v[176:179], v163 offset:32768
	ds_read_b128 v[180:183], v163 offset:33792
	ds_read_b128 v[184:187], v163 offset:34816
	ds_read_b128 v[188:191], v163 offset:35840
	ds_read_b128 v[192:195], v163 offset:36864
	ds_read_b128 v[196:199], v163 offset:37888
	ds_read_b128 v[200:203], v163 offset:38912
	ds_read_b128 v[210:213], v163 offset:39936
	global_load_lds_dwordx4 v[236:237], off
	v_lshl_add_u64 v[236:237], s[28:29], 0, v[148:149]
	s_mov_b32 m0, s79
	s_nop 0
	global_load_lds_dwordx4 v[236:237], off
	s_waitcnt vmcnt(8)
	s_waitcnt lgkmcnt(0)
	s_barrier
	s_setprio 1
	s_waitcnt lgkmcnt(0)
	v_mfma_f32_16x16x32_bf16 v[142:145], v[74:77], v[176:179], v[142:145]
	v_mfma_f32_16x16x32_bf16 v[138:141], v[82:85], v[176:179], v[138:141]
	v_mfma_f32_16x16x32_bf16 v[126:129], v[74:77], v[184:187], v[126:129]
	v_mfma_f32_16x16x32_bf16 v[122:125], v[82:85], v[184:187], v[122:125]
	v_mfma_f32_16x16x32_bf16 v[110:113], v[74:77], v[192:195], v[110:113]
	v_mfma_f32_16x16x32_bf16 v[106:109], v[82:85], v[192:195], v[106:109]
	v_mfma_f32_16x16x32_bf16 v[94:97], v[74:77], v[200:203], v[94:97]
	v_mfma_f32_16x16x32_bf16 v[90:93], v[82:85], v[200:203], v[90:93]
	v_mfma_f32_16x16x32_bf16 v[142:145], v[78:81], v[180:183], v[142:145]
	v_mfma_f32_16x16x32_bf16 v[138:141], v[86:89], v[180:183], v[138:141]
	v_mfma_f32_16x16x32_bf16 v[126:129], v[78:81], v[188:191], v[126:129]
	v_mfma_f32_16x16x32_bf16 v[122:125], v[86:89], v[188:191], v[122:125]
	v_mfma_f32_16x16x32_bf16 v[110:113], v[78:81], v[196:199], v[110:113]
	v_mfma_f32_16x16x32_bf16 v[106:109], v[86:89], v[196:199], v[106:109]
	v_mfma_f32_16x16x32_bf16 v[94:97], v[78:81], v[210:213], v[94:97]
	v_mfma_f32_16x16x32_bf16 v[90:93], v[86:89], v[210:213], v[90:93]
	s_setprio 0
	s_setprio 1
	v_mfma_f32_16x16x32_bf16 v[134:137], v[156:159], v[176:179], v[134:137]
	v_mfma_f32_16x16x32_bf16 v[130:133], v[168:171], v[176:179], v[130:133]
	v_mfma_f32_16x16x32_bf16 v[118:121], v[156:159], v[184:187], v[118:121]
	v_mfma_f32_16x16x32_bf16 v[114:117], v[168:171], v[184:187], v[114:117]
	v_mfma_f32_16x16x32_bf16 v[102:105], v[156:159], v[192:195], v[102:105]
	v_mfma_f32_16x16x32_bf16 v[98:101], v[168:171], v[192:195], v[98:101]
	v_mfma_f32_16x16x32_bf16 v[70:73], v[156:159], v[200:203], v[70:73]
	v_mfma_f32_16x16x32_bf16 v[66:69], v[168:171], v[200:203], v[66:69]
	v_mfma_f32_16x16x32_bf16 v[134:137], v[164:167], v[180:183], v[134:137]
	v_mfma_f32_16x16x32_bf16 v[130:133], v[172:175], v[180:183], v[130:133]
	v_mfma_f32_16x16x32_bf16 v[118:121], v[164:167], v[188:191], v[118:121]
	v_mfma_f32_16x16x32_bf16 v[114:117], v[172:175], v[188:191], v[114:117]
	v_mfma_f32_16x16x32_bf16 v[102:105], v[164:167], v[196:199], v[102:105]
	v_mfma_f32_16x16x32_bf16 v[98:101], v[172:175], v[196:199], v[98:101]
	v_mfma_f32_16x16x32_bf16 v[70:73], v[164:167], v[210:213], v[70:73]
	v_mfma_f32_16x16x32_bf16 v[66:69], v[172:175], v[210:213], v[66:69]
	s_setprio 0
	s_barrier
; #define PG8_STAGE(bufoff, gbase, voff) do { _Pragma("unroll") for (int _i = 0; _i < 2; ++_i) \
;         __builtin_amdgcn_global_load_lds((const unsigned*)((const char*)(gbase) + (voff)[_i]), (PG8_LAS unsigned*)(lds + (bufoff) + ldsw + _i * 8192), 16, 0, 0); } while (0)
; #define PG8_LDA(dst, b, h) do { _Pragma("unroll") for (int m = 0; m < 4; ++m) _Pragma("unroll") for (int k = 0; k < 2; ++k) dst[m][k] = *(const PG8_LAS bf16x8*)(lds + PG8_SA(b, h) + aoff + m * 2048 + k * 1024); } while (0)
; #define PG8_MMA(ai, bj, At, Bt) do { __builtin_amdgcn_s_setprio(1); _Pragma("unroll") for (int m = 0; m < 4; ++m) _Pragma("unroll") for (int n = 0; n < 2; ++n) _Pragma("unroll") for (int k = 0; k < 2; ++k) \
;         acc[ai][bj][m][n] = __builtin_amdgcn_mfma_f32_16x16x32_bf16(Bt[n][k], At[m][k], acc[ai][bj][m][n], 0, 0, 0); __builtin_amdgcn_s_setprio(0); } while (0)
; #define PG8_WAIT_V(n) asm volatile("s_waitcnt vmcnt(" #n ")" ::: "memory")
; #define PG8_WAIT_L(n) asm volatile("s_waitcnt lgkmcnt(" #n ")" ::: "memory")
; #define PG8_BAR __builtin_amdgcn_s_barrier()
; #define PG8_SCHED __builtin_amdgcn_sched_barrier(0)
; template <class Epi, class Sched, bool ALIGN_EPI = false, bool SP2 = false>
; __device__ __forceinline__ void gemm_phase(PG8_LAS unsigned char* lds, const Gemm g, const Sched& S, const Epi& E) {
;     ...
;             PG8_LDA(At, 1, 1); PG8_STAGE(PG8_SB(1, 0), b3, voffB); PG8_STAGE(PG8_SB(1, 1), b3 + hstep, voffB); PG8_STAGE(PG8_SA(1, 0), a3, voffA);
;             PG8_WAIT_V(8); PG8_WAIT_L(0); PG8_BAR; PG8_MMA(1, 0, At, B0); PG8_MMA(1, 1, At, B1); PG8_BAR; PG8_SCHED;
;     ...
;         }
;         if constexpr (ALIGN_EPI) { if (wr == 0) PG8_BAR; }
	s_add_i32 s28, s86, s62
	v_lshl_add_u64 v[204:205], v[204:205], 0, s[24:25]
	s_mov_b32 m0, s28
	ds_read_b128 v[176:179], v163 offset:49152
	ds_read_b128 v[180:183], v163 offset:50176
	ds_read_b128 v[184:187], v163 offset:51200
	ds_read_b128 v[188:191], v163 offset:52224
	ds_read_b128 v[192:195], v163 offset:53248
	ds_read_b128 v[196:199], v163 offset:54272
	ds_read_b128 v[200:203], v163 offset:55296
	ds_read_b128 v[210:213], v163 offset:56320
	global_load_lds_dwordx4 v[204:205], off
	v_lshl_add_u64 v[204:205], v[226:227], 0, s[24:25]
	s_add_i32 m0, s28, 0x2000
	s_add_i32 s28, s87, s62
	global_load_lds_dwordx4 v[204:205], off
	v_lshl_add_u64 v[204:205], v[228:229], 0, s[24:25]
	s_mov_b32 m0, s28
	s_nop 0
	global_load_lds_dwordx4 v[204:205], off
	v_lshl_add_u64 v[204:205], v[230:231], 0, s[24:25]
	s_add_i32 m0, s28, 0x2000
	s_nop 0
	global_load_lds_dwordx4 v[204:205], off
	v_lshl_add_u64 v[204:205], v[232:233], 0, s[24:25]
	s_mov_b32 m0, s80
	s_nop 0
	global_load_lds_dwordx4 v[204:205], off
	v_lshl_add_u64 v[204:205], v[234:235], 0, s[24:25]
	s_mov_b32 m0, s81
	s_nop 0
	global_load_lds_dwordx4 v[204:205], off
	s_waitcnt vmcnt(8)
	s_waitcnt lgkmcnt(0)
	s_barrier
	s_setprio 1
	s_waitcnt lgkmcnt(0)
	v_mfma_f32_16x16x32_bf16 v[62:65], v[74:77], v[176:179], v[62:65]
	v_mfma_f32_16x16x32_bf16 v[58:61], v[82:85], v[176:179], v[58:61]
	v_mfma_f32_16x16x32_bf16 v[46:49], v[74:77], v[184:187], v[46:49]
	v_mfma_f32_16x16x32_bf16 v[42:45], v[82:85], v[184:187], v[42:45]
	v_mfma_f32_16x16x32_bf16 v[30:33], v[74:77], v[192:195], v[30:33]
	v_mfma_f32_16x16x32_bf16 v[26:29], v[82:85], v[192:195], v[26:29]
	v_mfma_f32_16x16x32_bf16 v[14:17], v[74:77], v[200:203], v[14:17]
	v_mfma_f32_16x16x32_bf16 v[10:13], v[82:85], v[200:203], v[10:13]
	v_mfma_f32_16x16x32_bf16 v[62:65], v[78:81], v[180:183], v[62:65]
	v_mfma_f32_16x16x32_bf16 v[58:61], v[86:89], v[180:183], v[58:61]
	v_mfma_f32_16x16x32_bf16 v[46:49], v[78:81], v[188:191], v[46:49]
	v_mfma_f32_16x16x32_bf16 v[42:45], v[86:89], v[188:191], v[42:45]
	v_mfma_f32_16x16x32_bf16 v[30:33], v[78:81], v[196:199], v[30:33]
	v_mfma_f32_16x16x32_bf16 v[26:29], v[86:89], v[196:199], v[26:29]
	v_mfma_f32_16x16x32_bf16 v[14:17], v[78:81], v[210:213], v[14:17]
	v_mfma_f32_16x16x32_bf16 v[10:13], v[86:89], v[210:213], v[10:13]
	s_setprio 0
	s_setprio 1
	v_mfma_f32_16x16x32_bf16 v[54:57], v[156:159], v[176:179], v[54:57]
	v_mfma_f32_16x16x32_bf16 v[50:53], v[168:171], v[176:179], v[50:53]
	v_mfma_f32_16x16x32_bf16 v[38:41], v[156:159], v[184:187], v[38:41]
	v_mfma_f32_16x16x32_bf16 v[34:37], v[168:171], v[184:187], v[34:37]
	v_mfma_f32_16x16x32_bf16 v[22:25], v[156:159], v[192:195], v[22:25]
	v_mfma_f32_16x16x32_bf16 v[18:21], v[168:171], v[192:195], v[18:21]
	v_mfma_f32_16x16x32_bf16 v[6:9], v[156:159], v[200:203], v[6:9]
	v_mfma_f32_16x16x32_bf16 v[2:5], v[168:171], v[200:203], v[2:5]
	v_mfma_f32_16x16x32_bf16 v[54:57], v[164:167], v[180:183], v[54:57]
	v_mfma_f32_16x16x32_bf16 v[50:53], v[172:175], v[180:183], v[50:53]
	v_mfma_f32_16x16x32_bf16 v[38:41], v[164:167], v[188:191], v[38:41]
	v_mfma_f32_16x16x32_bf16 v[34:37], v[172:175], v[188:191], v[34:37]
	v_mfma_f32_16x16x32_bf16 v[22:25], v[164:167], v[196:199], v[22:25]
	v_mfma_f32_16x16x32_bf16 v[18:21], v[172:175], v[196:199], v[18:21]
	v_mfma_f32_16x16x32_bf16 v[6:9], v[164:167], v[210:213], v[6:9]
	v_mfma_f32_16x16x32_bf16 v[2:5], v[172:175], v[210:213], v[2:5]
	s_setprio 0
	s_barrier
	s_add_u32 s14, s14, 0x100
	s_addc_u32 s15, s15, 0
	s_add_u32 s47, s47, 0x100
	s_addc_u32 vcc_lo, vcc_lo, 0
	s_cmp_ge_u32 vcc_hi, s82
	s_mov_b32 s28, vcc_hi
	s_cbranch_scc0 .LBB0_410
	s_and_b64 vcc, exec, s[34:35]
	s_cbranch_vccz .LBB0_413
	s_barrier
